# speedup vs baseline: 1.0116x; 1.0076x over previous
; __device__ __forceinline__ void unpack8(u32x4 w, float* f) { f[0] = bflo(w.x); f[1] = bfhi(w.x); f[2] = bflo(w.y); f[3] = bfhi(w.y); f[4] = bflo(w.z); f[5] = bfhi(w.z); f[6] = bflo(w.w); f[7] = bfhi(w.w); }
; __device__ __forceinline__ void attn_unit(const bf16_t* __restrict__ Qb, const bf16_t* __restrict__ Kh, const bf16_t* __restrict__ Vh, bf16_t* __restrict__ Ob, float* __restrict__ ssq, char* lds, LAS unsigned char* ldsl, ...
;     ...
;   if (wid >= 4) __builtin_amdgcn_s_setprio(1);
;   float m_reg = -1e30f, l_reg = 0; f32x16 o[4]; bf16x8 qr[12];
;   char* qrope = lds + SHM_QR + wid * 4096 + lane * 16;
;   const bf16_t* Qw = Qb + (long)(wid * QBLK + r32) * QCOLS + hi * 8;
; #pragma unroll
;   for (int d0 = 0; d0 < 12; ++d0) qr[d0] = *reinterpret_cast<const bf16x8*>(Qw + d0 * 16);
;   {
;     float ss = 0.f;
; #pragma unroll
;     for (int d0 = 0; d0 < 12; ++d0) { float f[8]; unpack8(__builtin_bit_cast(u32x4, qr[d0]), f);
; #pragma unroll
;       for (int e = 0; e < 8; ++e) ss += f[e] * f[e]; }
;     { auto rr = __builtin_amdgcn_permlane32_swap(__float_as_uint(ss), __float_as_uint(ss), false, false); ss = __uint_as_float(rr[0]) + __uint_as_float(rr[1]); }
; __global__ void __launch_bounds__(512, 2) fwd_kernel(KP p) {
;     ...
;         for (int i = 0; ; ++i) {
;             int bh, qb;
;             if (G == 256) { if (i >= 5) break; bh = i * 8 + (b & 7); qb = b >> 3; }
;             else { const int U = i * G + b; if (U >= NSEQ * NH * 32) break; bh = U >> 5; qb = U & 31; }
;             const int sq = bh >> 3, h = bh & 7; const size_t row0 = (size_t)sq * SEQ + qb * 256;
;             att::attn_unit(Qb + row0 * QCOLS + h * DQK, Kb + (size_t)bh * SEQ * DQK, Vb + (size_t)bh * SEQ * DV, MIX + row0 * DM + h * DV, SSQA + row0 * NH + h, (char*)lds_raw, lds, p.in[I_GQ], ROPEC, ROPES, qb * 256, tid);
.LBB0_1007:
	s_mov_b64 s[8:9], -1
	s_and_b64 vcc, exec, s[0:1]
	s_cbranch_vccz .LBB0_1000
	s_and_saveexec_b64 s[0:1], s[38:39]
	s_setprio 1
	s_or_b64 exec, exec, s[0:1]
	s_ashr_i32 s0, s6, 3
	s_ashr_i32 s1, s0, 31
	s_lshl_b32 s49, s7, 8
	s_and_b32 s8, s6, 7
	s_lshl_b64 s[0:1], s[0:1], 13
	s_ashr_i32 s4, s49, 31
	s_add_u32 s0, s0, s49
	s_addc_u32 s1, s1, s4
	s_mul_i32 s4, s1, 0xc00
	s_mul_hi_u32 s5, s0, 0xc00
	s_add_i32 s5, s5, s4
	s_mul_i32 s4, s0, 0xc00
	s_add_u32 s4, s22, s4
	s_addc_u32 s5, s23, s5
	s_mul_i32 s7, s8, 0x180
	s_add_u32 s4, s4, s7
	s_addc_u32 s5, s5, 0
	v_lshl_add_u64 v[0:1], s[4:5], 0, v[160:161]
	v_mov_b32_e32 v171, v163
	v_lshl_add_u64 v[4:5], v[0:1], 0, v[170:171]
	global_load_dwordx4 v[32:35], v[4:5], off
	global_load_dwordx4 v[40:43], v[4:5], off offset:32
	global_load_dwordx4 v[44:47], v[4:5], off offset:64
	global_load_dwordx4 v[48:51], v[4:5], off offset:96
	global_load_dwordx4 v[28:31], v[4:5], off offset:128
	global_load_dwordx4 v[24:27], v[4:5], off offset:160
	global_load_dwordx4 v[16:19], v[4:5], off offset:192
	global_load_dwordx4 v[20:23], v[4:5], off offset:224
	global_load_dwordx4 v[8:11], v[4:5], off offset:256
	global_load_dwordx4 v[0:3], v[4:5], off offset:288
	global_load_dwordx4 v[12:15], v[4:5], off offset:320
	s_nop 0
	global_load_dwordx4 v[4:7], v[4:5], off offset:352
	s_nop 0
	global_load_dwordx4 v[118:121], v[164:165], off offset:16
	global_load_dwordx4 v[122:125], v[164:165], off
	s_mov_b32 s4, 0x800000
	s_ashr_i32 s7, s6, 31
	s_mul_i32 s31, s6, 0x300000
	v_readlane_b32 s16, v255, 15
	v_add_u32_e32 v217, 0x8000, v182
	s_mul_hi_i32 s9, s6, 0x300000
	v_readlane_b32 s17, v255, 16
	s_add_u32 s24, s16, s31
	s_addc_u32 s25, s17, s9
	v_add_u32_e32 v218, 0xa000, v182
	v_add_u32_e32 v219, 0xc000, v182
	s_lshl_b64 s[90:91], s[6:7], 21
	s_add_u32 s92, s20, s90
	s_addc_u32 s93, s21, s91
	v_add_u32_e32 v220, 0x2000, v182
	v_readfirstlane_b32 s6, v183
	v_add_u32_e32 v221, 0x2000, v183
	v_add_u32_e32 v222, 0x4000, v183
	s_mov_b32 s50, s48
	s_mov_b32 s51, s48
	s_mov_b32 s52, s48
	s_mov_b32 s53, s48
	s_mov_b32 s54, s48
	s_mov_b32 s55, s48
	s_mov_b32 s56, s48
	s_mov_b32 s57, s48
	s_mov_b32 s58, s48
	s_mov_b32 s59, s48
	s_mov_b32 s60, s48
	s_mov_b32 s61, s48
	s_mov_b32 s62, s48
	s_mov_b32 s63, s48
	v_mov_b32_e32 v171, 0
	s_waitcnt vmcnt(13)
	v_and_b32_e32 v115, 0xffff0000, v32
	v_lshlrev_b32_e32 v116, 16, v32
	v_mul_f32_e32 v38, v115, v115
	v_lshlrev_b32_e32 v114, 16, v33
	v_fmac_f32_e32 v38, v116, v116
	v_and_b32_e32 v113, 0xffff0000, v33
	v_fmac_f32_e32 v38, v114, v114
	v_lshlrev_b32_e32 v112, 16, v34
	v_fmac_f32_e32 v38, v113, v113
	v_and_b32_e32 v111, 0xffff0000, v34
	v_fmac_f32_e32 v38, v112, v112
	v_lshlrev_b32_e32 v110, 16, v35
	v_fmac_f32_e32 v38, v111, v111
	v_and_b32_e32 v109, 0xffff0000, v35
	v_fmac_f32_e32 v38, v110, v110
	v_fmac_f32_e32 v38, v109, v109
	s_waitcnt vmcnt(12)
	v_lshlrev_b32_e32 v102, 16, v40
	v_and_b32_e32 v101, 0xffff0000, v40
	v_fmac_f32_e32 v38, v102, v102
	v_lshlrev_b32_e32 v100, 16, v41
	v_fmac_f32_e32 v38, v101, v101
	v_and_b32_e32 v99, 0xffff0000, v41
	v_fmac_f32_e32 v38, v100, v100
	v_lshlrev_b32_e32 v98, 16, v42
	v_fmac_f32_e32 v38, v99, v99
	v_and_b32_e32 v97, 0xffff0000, v42
	v_fmac_f32_e32 v38, v98, v98
	v_lshlrev_b32_e32 v96, 16, v43
	v_fmac_f32_e32 v38, v97, v97
	v_and_b32_e32 v95, 0xffff0000, v43
	v_fmac_f32_e32 v38, v96, v96
	v_fmac_f32_e32 v38, v95, v95
	s_waitcnt vmcnt(11)
	v_lshlrev_b32_e32 v94, 16, v44
	v_and_b32_e32 v93, 0xffff0000, v44
	v_fmac_f32_e32 v38, v94, v94
	v_lshlrev_b32_e32 v92, 16, v45
	v_fmac_f32_e32 v38, v93, v93
	v_and_b32_e32 v91, 0xffff0000, v45
	v_fmac_f32_e32 v38, v92, v92
	v_lshlrev_b32_e32 v90, 16, v46
	v_fmac_f32_e32 v38, v91, v91
	v_and_b32_e32 v89, 0xffff0000, v46
	v_fmac_f32_e32 v38, v90, v90
	v_lshlrev_b32_e32 v88, 16, v47
	v_fmac_f32_e32 v38, v89, v89
	v_and_b32_e32 v87, 0xffff0000, v47
	v_fmac_f32_e32 v38, v88, v88
	v_fmac_f32_e32 v38, v87, v87
	s_waitcnt vmcnt(10)
	v_lshlrev_b32_e32 v74, 16, v48
	v_and_b32_e32 v73, 0xffff0000, v48
	v_fmac_f32_e32 v38, v74, v74
	v_lshlrev_b32_e32 v72, 16, v49
	v_fmac_f32_e32 v38, v73, v73
	v_and_b32_e32 v71, 0xffff0000, v49
	v_fmac_f32_e32 v38, v72, v72
	v_lshlrev_b32_e32 v70, 16, v50
	v_fmac_f32_e32 v38, v71, v71
	v_and_b32_e32 v43, 0xffff0000, v50
	v_fmac_f32_e32 v38, v70, v70
	v_lshlrev_b32_e32 v37, 16, v51
	v_fmac_f32_e32 v38, v43, v43
	v_and_b32_e32 v33, 0xffff0000, v51
	v_fmac_f32_e32 v38, v37, v37
	v_fmac_f32_e32 v38, v33, v33
	s_waitcnt vmcnt(9)
	v_lshlrev_b32_e32 v79, 16, v28
	v_and_b32_e32 v78, 0xffff0000, v28
	v_fmac_f32_e32 v38, v79, v79
	v_lshlrev_b32_e32 v77, 16, v29
	v_fmac_f32_e32 v38, v78, v78
	v_and_b32_e32 v76, 0xffff0000, v29
	v_fmac_f32_e32 v38, v77, v77
	v_lshlrev_b32_e32 v75, 16, v30
	v_fmac_f32_e32 v38, v76, v76
	v_and_b32_e32 v30, 0xffff0000, v30
	v_fmac_f32_e32 v38, v75, v75
	v_lshlrev_b32_e32 v29, 16, v31
	v_fmac_f32_e32 v38, v30, v30
	v_and_b32_e32 v28, 0xffff0000, v31
	v_fmac_f32_e32 v38, v29, v29
	v_fmac_f32_e32 v38, v28, v28
	s_waitcnt vmcnt(8)
	v_lshlrev_b32_e32 v83, 16, v24
	v_and_b32_e32 v82, 0xffff0000, v24
	v_fmac_f32_e32 v38, v83, v83
	v_lshlrev_b32_e32 v81, 16, v25
	v_fmac_f32_e32 v38, v82, v82
	v_and_b32_e32 v80, 0xffff0000, v25
	v_fmac_f32_e32 v38, v81, v81
	v_lshlrev_b32_e32 v31, 16, v26
	v_fmac_f32_e32 v38, v80, v80
	v_and_b32_e32 v26, 0xffff0000, v26
	v_fmac_f32_e32 v38, v31, v31
	v_lshlrev_b32_e32 v25, 16, v27
	v_fmac_f32_e32 v38, v26, v26
	v_and_b32_e32 v24, 0xffff0000, v27
	v_fmac_f32_e32 v38, v25, v25
	v_fmac_f32_e32 v38, v24, v24
	s_waitcnt vmcnt(7)
; __device__ __forceinline__ u32x4 pack8(const float* f) { u32x4 w; w.x = cvt_pk_bf16(f[0], f[1]); w.y = cvt_pk_bf16(f[2], f[3]); w.z = cvt_pk_bf16(f[4], f[5]); w.w = cvt_pk_bf16(f[6], f[7]); return w; }
; __device__ __forceinline__ void unpack8(u32x4 w, float* f) { f[0] = bflo(w.x); f[1] = bfhi(w.x); f[2] = bflo(w.y); f[3] = bfhi(w.y); f[4] = bflo(w.z); f[5] = bfhi(w.z); f[6] = bflo(w.w); f[7] = bfhi(w.w); }
; __device__ __forceinline__ void attn_unit(const bf16_t* __restrict__ Qb, const bf16_t* __restrict__ Kh, const bf16_t* __restrict__ Vh, bf16_t* __restrict__ Ob, float* __restrict__ ssq, char* lds, LAS unsigned char* ldsl, ...
;     ...
;     float ss = 0.f;
; #pragma unroll
;     for (int d0 = 0; d0 < 12; ++d0) { float f[8]; unpack8(__builtin_bit_cast(u32x4, qr[d0]), f);
; #pragma unroll
;       for (int e = 0; e < 8; ++e) ss += f[e] * f[e]; }
;     { auto rr = __builtin_amdgcn_permlane32_swap(__float_as_uint(ss), __float_as_uint(ss), false, false); ss = __uint_as_float(rr[0]) + __uint_as_float(rr[1]); }
;     const float rq = rsqrtf(ss * (1.f / DQK) + EPS);
; #pragma unroll
;     for (int d0 = 0; d0 < 8; ++d0) { float f[8]; unpack8(__builtin_bit_cast(u32x4, qr[d0]), f); const float* gp = qg + d0 * 16 + hi * 8;
; #pragma unroll
;       for (int e = 0; e < 8; ++e) f[e] *= rq * gp[e];
;       qr[d0] = __builtin_bit_cast(bf16x8, pack8(f)); }
	v_lshlrev_b32_e32 v86, 16, v16
	v_and_b32_e32 v85, 0xffff0000, v16
	v_fmac_f32_e32 v38, v86, v86
	v_lshlrev_b32_e32 v84, 16, v17
	v_fmac_f32_e32 v38, v85, v85
	v_and_b32_e32 v27, 0xffff0000, v17
	v_fmac_f32_e32 v38, v84, v84
	v_lshlrev_b32_e32 v17, 16, v18
	v_fmac_f32_e32 v38, v27, v27
	v_and_b32_e32 v16, 0xffff0000, v18
	v_fmac_f32_e32 v38, v17, v17
	v_lshlrev_b32_e32 v103, 16, v19
	v_fmac_f32_e32 v38, v16, v16
	v_and_b32_e32 v18, 0xffff0000, v19
	v_fmac_f32_e32 v38, v103, v103
	v_fmac_f32_e32 v38, v18, v18
	s_waitcnt vmcnt(6)
	v_lshlrev_b32_e32 v108, 16, v20
	v_and_b32_e32 v107, 0xffff0000, v20
	v_fmac_f32_e32 v38, v108, v108
	v_lshlrev_b32_e32 v106, 16, v21
	v_fmac_f32_e32 v38, v107, v107
	v_and_b32_e32 v105, 0xffff0000, v21
	v_fmac_f32_e32 v38, v106, v106
	v_lshlrev_b32_e32 v104, 16, v22
	v_fmac_f32_e32 v38, v105, v105
	v_and_b32_e32 v21, 0xffff0000, v22
	v_fmac_f32_e32 v38, v104, v104
	v_lshlrev_b32_e32 v20, 16, v23
	v_fmac_f32_e32 v38, v21, v21
	v_and_b32_e32 v19, 0xffff0000, v23
	v_fmac_f32_e32 v38, v20, v20
	s_waitcnt vmcnt(5)
	v_lshlrev_b32_e32 v58, 16, v11
	v_and_b32_e32 v56, 0xffff0000, v11
	v_lshlrev_b32_e32 v62, 16, v10
	v_and_b32_e32 v60, 0xffff0000, v10
	s_waitcnt vmcnt(3)
	v_lshlrev_b32_e32 v11, 16, v12
	v_lshlrev_b32_e32 v10, 16, v8
	v_fmac_f32_e32 v38, v19, v19
	v_pk_mul_f32 v[136:137], v[10:11], v[10:11]
	v_and_b32_e32 v69, 0xffff0000, v12
	v_and_b32_e32 v68, 0xffff0000, v8
	v_lshlrev_b32_e32 v36, 16, v3
	v_and_b32_e32 v32, 0xffff0000, v3
	v_lshlrev_b32_e32 v67, 16, v13
	v_lshlrev_b32_e32 v66, 16, v9
	v_and_b32_e32 v64, 0xffff0000, v9
	v_add_f32_e32 v3, v136, v38
	v_pk_mul_f32 v[8:9], v[68:69], v[68:69]
	v_pk_mul_f32 v[132:133], v[66:67], v[66:67]
	v_and_b32_e32 v65, 0xffff0000, v13
	v_add_f32_e32 v3, v8, v3
	v_lshlrev_b32_e32 v63, 16, v14
	v_pk_mul_f32 v[134:135], v[64:65], v[64:65]
	v_add_f32_e32 v3, v132, v3
	v_pk_mul_f32 v[130:131], v[62:63], v[62:63]
	v_and_b32_e32 v61, 0xffff0000, v14
	v_add_f32_e32 v3, v134, v3
	v_lshlrev_b32_e32 v59, 16, v15
	v_and_b32_e32 v57, 0xffff0000, v15
	v_pk_mul_f32 v[14:15], v[60:61], v[60:61]
	v_add_f32_e32 v3, v130, v3
	v_pk_mul_f32 v[126:127], v[58:59], v[58:59]
	v_add_f32_e32 v3, v14, v3
	v_pk_mul_f32 v[128:129], v[56:57], v[56:57]
	v_add_f32_e32 v3, v126, v3
	s_waitcnt vmcnt(2)
	v_lshlrev_b32_e32 v55, 16, v4
	v_lshlrev_b32_e32 v54, 16, v0
	v_add_f32_e32 v8, v128, v3
	v_pk_mul_f32 v[12:13], v[54:55], v[54:55]
	v_and_b32_e32 v49, 0xffff0000, v4
	v_and_b32_e32 v48, 0xffff0000, v0
	v_add_lshl_u32 v40, v176, s49, 5
	v_lshlrev_b32_e32 v47, 16, v5
	v_lshlrev_b32_e32 v46, 16, v1
	v_and_b32_e32 v45, 0xffff0000, v5
	v_and_b32_e32 v44, 0xffff0000, v1
	v_add_f32_e32 v5, v12, v8
	v_pk_mul_f32 v[0:1], v[48:49], v[48:49]
	v_ashrrev_i32_e32 v41, 31, v40
	v_add_f32_e32 v0, v0, v5
	v_lshlrev_b64 v[40:41], 2, v[40:41]
	v_fmac_f32_e32 v0, v46, v46
	v_lshl_add_u64 v[52:53], v[166:167], 0, v[40:41]
	v_lshl_add_u64 v[50:51], v[168:169], 0, v[40:41]
	v_lshlrev_b32_e32 v40, 16, v2
	v_fmac_f32_e32 v0, v44, v44
	v_and_b32_e32 v38, 0xffff0000, v2
	v_fmac_f32_e32 v0, v40, v40
	v_fmac_f32_e32 v0, v38, v38
	v_fmac_f32_e32 v0, v36, v36
	v_fmac_f32_e32 v0, v32, v32
	v_add_f32_e32 v0, v137, v0
	v_add_f32_e32 v0, v9, v0
	v_add_f32_e32 v0, v133, v0
	v_add_f32_e32 v0, v135, v0
	v_add_f32_e32 v0, v131, v0
	v_add_f32_e32 v0, v15, v0
	v_add_f32_e32 v0, v127, v0
	v_add_f32_e32 v0, v129, v0
	v_and_b32_e32 v34, 0xffff0000, v7
	v_lshlrev_b32_e32 v35, 16, v7
	v_lshlrev_b32_e32 v41, 16, v6
	v_and_b32_e32 v39, 0xffff0000, v6
	v_mov_b32_e32 v6, v45
	v_mov_b32_e32 v7, v47
	v_add_f32_e32 v0, v13, v0
	v_pk_mul_f32 v[6:7], v[6:7], v[6:7]
	v_add_f32_e32 v0, v1, v0
	v_mov_b32_e32 v2, v39
	v_mov_b32_e32 v3, v41
	v_add_f32_e32 v0, v7, v0
	v_pk_mul_f32 v[2:3], v[2:3], v[2:3]
	v_add_f32_e32 v0, v6, v0
	v_add_f32_e32 v0, v3, v0
	v_pk_mul_f32 v[22:23], v[34:35], v[34:35]
	v_add_f32_e32 v0, v2, v0
	v_add_f32_e32 v0, v23, v0
	v_add_f32_e32 v0, v22, v0
	v_mov_b32_e32 v1, v0
	s_nop 1
	v_permlane32_swap_b32_e32 v0, v1
	v_add_f32_e32 v0, v0, v1
	v_fmamk_f32 v0, v0, 0x3baaaaab, v197
	v_cmp_gt_f32_e32 vcc, s4, v0
	v_mul_f32_e32 v1, 0x4b800000, v0
	v_readfirstlane_b32 s4, v217
	v_cndmask_b32_e32 v0, v0, v1, vcc
	v_rsq_f32_e32 v0, v0
	s_mov_b32 m0, s4
	v_readfirstlane_b32 s4, v218
	s_mov_b32 s49, s48
	v_mul_f32_e32 v1, 0x45800000, v0
	v_cndmask_b32_e32 v42, v0, v1, vcc
	s_waitcnt vmcnt(0)
	v_mul_f32_e32 v0, v122, v42
	v_mul_f32_e32 v1, v123, v42
	v_mul_f32_e32 v2, v124, v42
	v_mul_f32_e32 v3, v125, v42
	v_mul_f32_e32 v4, v118, v42
	v_mul_f32_e32 v5, v119, v42
	v_mul_f32_e32 v6, v120, v42
	v_mul_f32_e32 v7, v121, v42
	v_mul_f32_e32 v0, v0, v116
	v_mul_f32_e32 v1, v1, v115
	v_mul_f32_e32 v2, v2, v114
	v_mul_f32_e32 v3, v3, v113
	v_mul_f32_e32 v4, v4, v112
	v_mul_f32_e32 v5, v5, v111
	v_mul_f32_e32 v6, v6, v110
	v_mul_f32_e32 v7, v7, v109
	v_cvt_pk_bf16_f32 v128, v0, v1
	v_cvt_pk_bf16_f32 v129, v2, v3
	v_cvt_pk_bf16_f32 v130, v4, v5
	v_cvt_pk_bf16_f32 v131, v6, v7
	global_load_dwordx4 v[0:3], v[164:165], off offset:80
	global_load_dwordx4 v[4:7], v[164:165], off offset:64
	v_pk_mul_f32 v[8:9], v[42:43], v[10:11] op_sel_hi:[0,1]
	v_pk_mul_f32 v[68:69], v[42:43], v[68:69] op_sel_hi:[0,1]
	s_waitcnt vmcnt(1)
	v_mul_f32_e32 v0, v42, v0
	s_waitcnt vmcnt(0)
	v_mul_f32_e32 v4, v42, v4
	v_mul_f32_e32 v5, v42, v5
	v_mul_f32_e32 v6, v42, v6
	v_mul_f32_e32 v7, v42, v7
	v_mul_f32_e32 v1, v42, v1
	v_mul_f32_e32 v2, v42, v2
	v_mul_f32_e32 v3, v42, v3
	v_mul_f32_e32 v4, v4, v102
	v_mul_f32_e32 v5, v5, v101
	v_mul_f32_e32 v6, v6, v100
	v_mul_f32_e32 v7, v7, v99
	v_mul_f32_e32 v0, v0, v98
	v_mul_f32_e32 v1, v1, v97
	v_mul_f32_e32 v2, v2, v96
	v_mul_f32_e32 v3, v3, v95
	v_cvt_pk_bf16_f32 v132, v4, v5
	v_cvt_pk_bf16_f32 v133, v6, v7
	v_cvt_pk_bf16_f32 v134, v0, v1
	v_cvt_pk_bf16_f32 v135, v2, v3
	global_load_dwordx4 v[0:3], v[164:165], off offset:144
	global_load_dwordx4 v[4:7], v[164:165], off offset:128
	s_waitcnt vmcnt(1)
; __device__ __forceinline__ u32x4 pack8(const float* f) { u32x4 w; w.x = cvt_pk_bf16(f[0], f[1]); w.y = cvt_pk_bf16(f[2], f[3]); w.z = cvt_pk_bf16(f[4], f[5]); w.w = cvt_pk_bf16(f[6], f[7]); return w; }
; __device__ __forceinline__ void unpack8(u32x4 w, float* f) { f[0] = bflo(w.x); f[1] = bfhi(w.x); f[2] = bflo(w.y); f[3] = bfhi(w.y); f[4] = bflo(w.z); f[5] = bfhi(w.z); f[6] = bflo(w.w); f[7] = bfhi(w.w); }
; __device__ __forceinline__ void attn_unit(const bf16_t* __restrict__ Qb, const bf16_t* __restrict__ Kh, const bf16_t* __restrict__ Vh, bf16_t* __restrict__ Ob, float* __restrict__ ssq, char* lds, LAS unsigned char* ldsl, ...
;     ...
;     for (int d0 = 0; d0 < 8; ++d0) { float f[8]; unpack8(__builtin_bit_cast(u32x4, qr[d0]), f); const float* gp = qg + d0 * 16 + hi * 8;
; #pragma unroll
;       for (int e = 0; e < 8; ++e) f[e] *= rq * gp[e];
;       qr[d0] = __builtin_bit_cast(bf16x8, pack8(f)); }
;     const int pos = pos0 + wid * QBLK + r32;
; #pragma unroll
;     for (int dd = 0; dd < 2; ++dd) { float x1[8], x2[8], y1[8], y2[8]; unpack8(__builtin_bit_cast(u32x4, qr[8 + dd]), x1); unpack8(__builtin_bit_cast(u32x4, qr[10 + dd]), x2);
;       const float* g1 = qg + 128 + dd * 16 + hi * 8; const float* g2 = g1 + 32; const float* cp_ = ropec + pos * 32 + dd * 16 + hi * 8; const float* sp_ = ropes + pos * 32 + dd * 16 + hi * 8;
; #pragma unroll
;       for (int e = 0; e < 8; ++e) { const float a = x1[e] * rq * g1[e], b = x2[e] * rq * g2[e]; y1[e] = a * cp_[e] - b * sp_[e]; y2[e] = b * cp_[e] + a * sp_[e]; }
;       *(u32x4*)(qrope + dd * 1024) = pack8(y1); *(u32x4*)(qrope + (2 + dd) * 1024) = pack8(y2); }
	v_mul_f32_e32 v0, v42, v0
	s_waitcnt vmcnt(0)
	v_mul_f32_e32 v4, v42, v4
	v_mul_f32_e32 v5, v42, v5
	v_mul_f32_e32 v6, v42, v6
	v_mul_f32_e32 v7, v42, v7
	v_mul_f32_e32 v1, v42, v1
	v_mul_f32_e32 v2, v42, v2
	v_mul_f32_e32 v3, v42, v3
	v_mul_f32_e32 v4, v4, v94
	v_mul_f32_e32 v5, v5, v93
	v_mul_f32_e32 v6, v6, v92
	v_mul_f32_e32 v7, v7, v91
	v_mul_f32_e32 v0, v0, v90
	v_mul_f32_e32 v1, v1, v89
	v_mul_f32_e32 v2, v2, v88
	v_mul_f32_e32 v3, v3, v87
	v_cvt_pk_bf16_f32 v136, v4, v5
	v_cvt_pk_bf16_f32 v137, v6, v7
	v_cvt_pk_bf16_f32 v138, v0, v1
	v_cvt_pk_bf16_f32 v139, v2, v3
	global_load_dwordx4 v[0:3], v[164:165], off offset:208
	global_load_dwordx4 v[4:7], v[164:165], off offset:192
	s_waitcnt vmcnt(1)
	v_mul_f32_e32 v0, v42, v0
	s_waitcnt vmcnt(0)
	v_mul_f32_e32 v4, v42, v4
	v_mul_f32_e32 v5, v42, v5
	v_mul_f32_e32 v6, v42, v6
	v_mul_f32_e32 v7, v42, v7
	v_mul_f32_e32 v1, v42, v1
	v_mul_f32_e32 v2, v42, v2
	v_mul_f32_e32 v3, v42, v3
	v_mul_f32_e32 v4, v4, v74
	v_mul_f32_e32 v5, v5, v73
	v_mul_f32_e32 v6, v6, v72
	v_mul_f32_e32 v7, v7, v71
	v_mul_f32_e32 v0, v0, v70
	v_mul_f32_e32 v1, v1, v43
	v_mul_f32_e32 v2, v2, v37
	v_mul_f32_e32 v3, v3, v33
	v_cvt_pk_bf16_f32 v156, v4, v5
	v_cvt_pk_bf16_f32 v157, v6, v7
	v_cvt_pk_bf16_f32 v158, v0, v1
	v_cvt_pk_bf16_f32 v159, v2, v3
	global_load_dwordx4 v[0:3], v[164:165], off offset:272
	global_load_dwordx4 v[4:7], v[164:165], off offset:256
	s_waitcnt vmcnt(1)
	v_mul_f32_e32 v0, v42, v0
	s_waitcnt vmcnt(0)
	v_mul_f32_e32 v4, v42, v4
	v_mul_f32_e32 v5, v42, v5
	v_mul_f32_e32 v6, v42, v6
	v_mul_f32_e32 v7, v42, v7
	v_mul_f32_e32 v1, v42, v1
	v_mul_f32_e32 v2, v42, v2
	v_mul_f32_e32 v3, v42, v3
	v_mul_f32_e32 v4, v4, v79
	v_mul_f32_e32 v5, v5, v78
	v_mul_f32_e32 v6, v6, v77
	v_mul_f32_e32 v7, v7, v76
	v_mul_f32_e32 v0, v0, v75
	v_mul_f32_e32 v1, v1, v30
	v_mul_f32_e32 v2, v2, v29
	v_mul_f32_e32 v3, v3, v28
	v_cvt_pk_bf16_f32 v152, v4, v5
	v_cvt_pk_bf16_f32 v153, v6, v7
	v_cvt_pk_bf16_f32 v154, v0, v1
	v_cvt_pk_bf16_f32 v155, v2, v3
	global_load_dwordx4 v[0:3], v[164:165], off offset:336
	global_load_dwordx4 v[4:7], v[164:165], off offset:320
	s_waitcnt vmcnt(1)
	v_mul_f32_e32 v0, v42, v0
	s_waitcnt vmcnt(0)
	v_mul_f32_e32 v4, v42, v4
	v_mul_f32_e32 v5, v42, v5
	v_mul_f32_e32 v6, v42, v6
	v_mul_f32_e32 v7, v42, v7
	v_mul_f32_e32 v1, v42, v1
	v_mul_f32_e32 v2, v42, v2
	v_mul_f32_e32 v3, v42, v3
	v_mul_f32_e32 v4, v4, v83
	v_mul_f32_e32 v5, v5, v82
	v_mul_f32_e32 v6, v6, v81
	v_mul_f32_e32 v7, v7, v80
	v_mul_f32_e32 v0, v0, v31
	v_mul_f32_e32 v1, v1, v26
	v_mul_f32_e32 v2, v2, v25
	v_mul_f32_e32 v3, v3, v24
	v_cvt_pk_bf16_f32 v148, v4, v5
	v_cvt_pk_bf16_f32 v149, v6, v7
	v_cvt_pk_bf16_f32 v150, v0, v1
	v_cvt_pk_bf16_f32 v151, v2, v3
	global_load_dwordx4 v[0:3], v[164:165], off offset:400
	global_load_dwordx4 v[4:7], v[164:165], off offset:384
	s_waitcnt vmcnt(1)
	v_mul_f32_e32 v0, v42, v0
	s_waitcnt vmcnt(0)
	v_mul_f32_e32 v4, v42, v4
	v_mul_f32_e32 v5, v42, v5
	v_mul_f32_e32 v6, v42, v6
	v_mul_f32_e32 v7, v42, v7
	v_mul_f32_e32 v1, v42, v1
	v_mul_f32_e32 v2, v42, v2
	v_mul_f32_e32 v3, v42, v3
	v_mul_f32_e32 v4, v4, v86
	v_mul_f32_e32 v5, v5, v85
	v_mul_f32_e32 v6, v6, v84
	v_mul_f32_e32 v7, v7, v27
	v_mul_f32_e32 v0, v0, v17
	v_mul_f32_e32 v1, v1, v16
	v_mul_f32_e32 v2, v2, v103
	v_mul_f32_e32 v3, v3, v18
	v_cvt_pk_bf16_f32 v144, v4, v5
	v_cvt_pk_bf16_f32 v145, v6, v7
	v_cvt_pk_bf16_f32 v146, v0, v1
	v_cvt_pk_bf16_f32 v147, v2, v3
	global_load_dwordx4 v[0:3], v[164:165], off offset:464
	global_load_dwordx4 v[4:7], v[164:165], off offset:448
	s_waitcnt vmcnt(1)
	v_mul_f32_e32 v0, v42, v0
	s_waitcnt vmcnt(0)
	v_mul_f32_e32 v4, v42, v4
	v_mul_f32_e32 v5, v42, v5
	v_mul_f32_e32 v6, v42, v6
	v_mul_f32_e32 v7, v42, v7
	v_mul_f32_e32 v1, v42, v1
	v_mul_f32_e32 v2, v42, v2
	v_mul_f32_e32 v3, v42, v3
	v_mul_f32_e32 v4, v4, v108
	v_mul_f32_e32 v5, v5, v107
	v_mul_f32_e32 v6, v6, v106
	v_mul_f32_e32 v7, v7, v105
	v_mul_f32_e32 v0, v0, v104
	v_mul_f32_e32 v1, v1, v21
	v_mul_f32_e32 v2, v2, v20
	v_mul_f32_e32 v3, v3, v19
	v_cvt_pk_bf16_f32 v140, v4, v5
	v_cvt_pk_bf16_f32 v141, v6, v7
	v_cvt_pk_bf16_f32 v142, v0, v1
	v_cvt_pk_bf16_f32 v143, v2, v3
	global_load_dwordx4 v[0:3], v[164:165], off offset:528
	global_load_dwordx4 v[16:19], v[164:165], off offset:512
	global_load_dwordx4 v[4:7], v[164:165], off offset:656
	global_load_dwordx4 v[20:23], v[164:165], off offset:640
	s_waitcnt vmcnt(2)
	v_mov_b32_e32 v10, v16
	s_waitcnt vmcnt(0)
	v_mov_b32_e32 v11, v20
	v_pk_mul_f32 v[70:71], v[8:9], v[10:11]
	global_load_dwordx4 v[8:11], v[52:53], off offset:16
	global_load_dwordx4 v[24:27], v[52:53], off
	global_load_dwordx4 v[12:15], v[50:51], off offset:16
	global_load_dwordx4 v[28:31], v[50:51], off
	v_mov_b32_e32 v20, v17
	v_pk_mul_f32 v[16:17], v[68:69], v[20:21]
	s_waitcnt vmcnt(2)
	v_mov_b32_e32 v72, v24
	s_waitcnt vmcnt(0)
; __device__ __forceinline__ u32x4 pack8(const float* f) { u32x4 w; w.x = cvt_pk_bf16(f[0], f[1]); w.y = cvt_pk_bf16(f[2], f[3]); w.z = cvt_pk_bf16(f[4], f[5]); w.w = cvt_pk_bf16(f[6], f[7]); return w; }
; __device__ __forceinline__ void unpack8(u32x4 w, float* f) { f[0] = bflo(w.x); f[1] = bfhi(w.x); f[2] = bflo(w.y); f[3] = bfhi(w.y); f[4] = bflo(w.z); f[5] = bfhi(w.z); f[6] = bflo(w.w); f[7] = bfhi(w.w); }
; __device__ __forceinline__ void attn_unit(const bf16_t* __restrict__ Qb, const bf16_t* __restrict__ Kh, const bf16_t* __restrict__ Vh, bf16_t* __restrict__ Ob, float* __restrict__ ssq, char* lds, LAS unsigned char* ldsl, ...
;     ...
;     const int pos = pos0 + wid * QBLK + r32;
; #pragma unroll
;     for (int dd = 0; dd < 2; ++dd) { float x1[8], x2[8], y1[8], y2[8]; unpack8(__builtin_bit_cast(u32x4, qr[8 + dd]), x1); unpack8(__builtin_bit_cast(u32x4, qr[10 + dd]), x2);
;       const float* g1 = qg + 128 + dd * 16 + hi * 8; const float* g2 = g1 + 32; const float* cp_ = ropec + pos * 32 + dd * 16 + hi * 8; const float* sp_ = ropes + pos * 32 + dd * 16 + hi * 8;
; #pragma unroll
;       for (int e = 0; e < 8; ++e) { const float a = x1[e] * rq * g1[e], b = x2[e] * rq * g2[e]; y1[e] = a * cp_[e] - b * sp_[e]; y2[e] = b * cp_[e] + a * sp_[e]; }
;       *(u32x4*)(qrope + dd * 1024) = pack8(y1); *(u32x4*)(qrope + (2 + dd) * 1024) = pack8(y2); }
	v_mov_b32_e32 v73, v28
	v_pk_mul_f32 v[72:73], v[70:71], v[72:73]
	s_nop 0
	v_sub_f32_e32 v33, v72, v73
	v_mov_b32_e32 v72, v28
	v_mov_b32_e32 v73, v24
	v_mov_b32_e32 v28, v25
	v_mov_b32_e32 v24, v29
	v_pk_mul_f32 v[20:21], v[16:17], v[28:29]
	v_pk_mul_f32 v[16:17], v[16:17], v[24:25]
	v_sub_f32_e32 v28, v20, v21
	v_add_f32_e32 v24, v17, v16
	v_pk_mul_f32 v[16:17], v[42:43], v[66:67] op_sel_hi:[0,1]
	v_mov_b32_e32 v20, v18
	v_mov_b32_e32 v21, v22
	v_pk_mul_f32 v[16:17], v[16:17], v[20:21]
	v_mov_b32_e32 v20, v26
	v_mov_b32_e32 v21, v30
	v_pk_mul_f32 v[20:21], v[16:17], v[20:21]
	v_mov_b32_e32 v22, v19
	v_sub_f32_e32 v25, v20, v21
	v_mov_b32_e32 v20, v30
	v_mov_b32_e32 v21, v26
	v_pk_mul_f32 v[16:17], v[16:17], v[20:21]
	v_mov_b32_e32 v30, v27
	v_add_f32_e32 v20, v17, v16
	v_pk_mul_f32 v[16:17], v[42:43], v[64:65] op_sel_hi:[0,1]
	v_pk_mul_f32 v[16:17], v[16:17], v[22:23]
	v_mov_b32_e32 v26, v31
	v_pk_mul_f32 v[18:19], v[16:17], v[30:31]
	v_pk_mul_f32 v[16:17], v[16:17], v[26:27]
	v_sub_f32_e32 v21, v18, v19
	v_add_f32_e32 v22, v17, v16
	v_pk_mul_f32 v[16:17], v[42:43], v[62:63] op_sel_hi:[0,1]
	v_mov_b32_e32 v18, v0
	v_mov_b32_e32 v19, v4
	v_pk_mul_f32 v[16:17], v[16:17], v[18:19]
	v_mov_b32_e32 v18, v8
	v_mov_b32_e32 v19, v12
	v_pk_mul_f32 v[18:19], v[16:17], v[18:19]
	v_mov_b32_e32 v4, v1
	v_sub_f32_e32 v23, v18, v19
	v_mov_b32_e32 v18, v12
	v_mov_b32_e32 v19, v8
	v_pk_mul_f32 v[16:17], v[16:17], v[18:19]
	v_mov_b32_e32 v12, v9
	v_add_f32_e32 v18, v17, v16
	v_pk_mul_f32 v[16:17], v[42:43], v[60:61] op_sel_hi:[0,1]
	v_pk_mul_f32 v[0:1], v[16:17], v[4:5]
	v_mov_b32_e32 v8, v13
	v_pk_mul_f32 v[4:5], v[0:1], v[12:13]
	v_pk_mul_f32 v[0:1], v[0:1], v[8:9]
	v_sub_f32_e32 v12, v4, v5
	v_add_f32_e32 v8, v1, v0
	v_pk_mul_f32 v[0:1], v[42:43], v[58:59] op_sel_hi:[0,1]
	v_mov_b32_e32 v4, v2
	v_mov_b32_e32 v5, v6
	v_pk_mul_f32 v[0:1], v[0:1], v[4:5]
	v_mov_b32_e32 v4, v10
	v_mov_b32_e32 v5, v14
	v_pk_mul_f32 v[4:5], v[0:1], v[4:5]
	v_mov_b32_e32 v6, v3
	v_sub_f32_e32 v9, v4, v5
	v_mov_b32_e32 v4, v14
	v_mov_b32_e32 v5, v10
	v_pk_mul_f32 v[0:1], v[0:1], v[4:5]
	v_mov_b32_e32 v14, v11
	v_add_f32_e32 v4, v1, v0
	v_pk_mul_f32 v[0:1], v[42:43], v[56:57] op_sel_hi:[0,1]
	v_pk_mul_f32 v[0:1], v[0:1], v[6:7]
	v_mov_b32_e32 v10, v15
	v_pk_mul_f32 v[2:3], v[0:1], v[14:15]
	v_pk_mul_f32 v[0:1], v[0:1], v[10:11]
	v_sub_f32_e32 v3, v2, v3
	v_pk_mul_f32 v[70:71], v[70:71], v[72:73]
	v_add_f32_e32 v5, v1, v0
	v_cvt_pk_bf16_f32 v0, v33, v28
	v_cvt_pk_bf16_f32 v1, v25, v21
	v_cvt_pk_bf16_f32 v2, v23, v12
	v_cvt_pk_bf16_f32 v3, v9, v3
	v_add_f32_e32 v37, v71, v70
	ds_write_b128 v215, v[0:3]
	v_cvt_pk_bf16_f32 v0, v37, v24
	v_cvt_pk_bf16_f32 v1, v20, v22
	v_cvt_pk_bf16_f32 v2, v18, v8
	v_cvt_pk_bf16_f32 v3, v4, v5
	ds_write_b128 v215, v[0:3] offset:2048
	global_load_dwordx4 v[0:3], v[164:165], off offset:592
	global_load_dwordx4 v[16:19], v[164:165], off offset:576
	global_load_dwordx4 v[4:7], v[164:165], off offset:720
	global_load_dwordx4 v[20:23], v[164:165], off offset:704
	v_pk_mul_f32 v[8:9], v[42:43], v[54:55] op_sel_hi:[0,1]
	v_mov_b32_e32 v37, v35
	v_mov_b32_e32 v33, v34
	s_waitcnt vmcnt(2)
	v_mov_b32_e32 v10, v16
	s_waitcnt vmcnt(0)
	v_mov_b32_e32 v11, v20
	v_pk_mul_f32 v[54:55], v[8:9], v[10:11]
	global_load_dwordx4 v[8:11], v[52:53], off offset:80
	global_load_dwordx4 v[24:27], v[52:53], off offset:64
	global_load_dwordx4 v[12:15], v[50:51], off offset:80
	global_load_dwordx4 v[28:31], v[50:51], off offset:64
	v_mov_b32_e32 v20, v17
	s_waitcnt vmcnt(2)
	v_mov_b32_e32 v50, v24
	s_waitcnt vmcnt(0)
	v_mov_b32_e32 v51, v28
	v_pk_mul_f32 v[50:51], v[54:55], v[50:51]
	s_nop 0
	v_sub_f32_e32 v43, v50, v51
	v_pk_mul_f32 v[48:49], v[42:43], v[48:49] op_sel_hi:[0,1]
	v_mov_b32_e32 v50, v28
	v_mov_b32_e32 v51, v24
	v_pk_mul_f32 v[16:17], v[48:49], v[20:21]
	v_mov_b32_e32 v28, v25
	v_mov_b32_e32 v24, v29
	v_pk_mul_f32 v[20:21], v[16:17], v[28:29]
	v_pk_mul_f32 v[16:17], v[16:17], v[24:25]
	v_sub_f32_e32 v28, v20, v21
	v_add_f32_e32 v24, v17, v16
	v_pk_mul_f32 v[16:17], v[42:43], v[46:47] op_sel_hi:[0,1]
	v_mov_b32_e32 v20, v18
	v_mov_b32_e32 v21, v22
	v_pk_mul_f32 v[16:17], v[16:17], v[20:21]
	v_mov_b32_e32 v20, v26
	v_mov_b32_e32 v21, v30
	v_pk_mul_f32 v[20:21], v[16:17], v[20:21]
	v_mov_b32_e32 v22, v19
	v_sub_f32_e32 v25, v20, v21
	v_mov_b32_e32 v20, v30
	v_mov_b32_e32 v21, v26
	v_pk_mul_f32 v[16:17], v[16:17], v[20:21]
	v_mov_b32_e32 v30, v27
	v_add_f32_e32 v20, v17, v16
	v_pk_mul_f32 v[16:17], v[42:43], v[44:45] op_sel_hi:[0,1]
	v_pk_mul_f32 v[16:17], v[16:17], v[22:23]
	v_mov_b32_e32 v26, v31
	v_pk_mul_f32 v[18:19], v[16:17], v[30:31]
	v_pk_mul_f32 v[16:17], v[16:17], v[26:27]
	v_sub_f32_e32 v21, v18, v19
	v_add_f32_e32 v22, v17, v16
	v_pk_mul_f32 v[16:17], v[42:43], v[40:41] op_sel_hi:[0,1]
	v_mov_b32_e32 v18, v0
	v_mov_b32_e32 v19, v4
	v_pk_mul_f32 v[16:17], v[16:17], v[18:19]
	v_mov_b32_e32 v18, v8
	v_mov_b32_e32 v19, v12
	v_pk_mul_f32 v[18:19], v[16:17], v[18:19]
	v_mov_b32_e32 v4, v1
	v_sub_f32_e32 v23, v18, v19
	v_mov_b32_e32 v18, v12
	v_mov_b32_e32 v19, v8
	v_pk_mul_f32 v[16:17], v[16:17], v[18:19]
	v_mov_b32_e32 v12, v9
	v_add_f32_e32 v18, v17, v16
	v_pk_mul_f32 v[16:17], v[42:43], v[38:39] op_sel_hi:[0,1]
	v_pk_mul_f32 v[0:1], v[16:17], v[4:5]
	v_mov_b32_e32 v8, v13
	v_pk_mul_f32 v[4:5], v[0:1], v[12:13]
	v_pk_mul_f32 v[0:1], v[0:1], v[8:9]
	v_sub_f32_e32 v12, v4, v5
	v_add_f32_e32 v8, v1, v0
	v_pk_mul_f32 v[0:1], v[42:43], v[36:37] op_sel_hi:[0,1]
	v_mov_b32_e32 v4, v2
	v_mov_b32_e32 v5, v6
	v_pk_mul_f32 v[0:1], v[0:1], v[4:5]
	v_mov_b32_e32 v4, v10
	v_mov_b32_e32 v5, v14
	v_pk_mul_f32 v[4:5], v[0:1], v[4:5]
	v_mov_b32_e32 v6, v3
	v_sub_f32_e32 v9, v4, v5
; __device__ __forceinline__ int v_rd_base(int lane) { return ((lane & 3) << 3) | (((lane >> 2) & 3) << 6) | (((lane >> 4) & 1) << 5) | (((lane >> 5) & 1) << 8); }
; __device__ __forceinline__ void qkt(f32x16& p0, f32x16& p1, const char* Ks, const bf16x8* qr, const char* qrope, int r32, int hi) {
;   p0 = f32x16{}; p1 = f32x16{};
;   for (int d0 = 0; d0 < 8; ++d0) { int cb = (d0 * 16 + hi * 8) * 2;
;     bf16x8 b0 = *reinterpret_cast<const bf16x8*>(Ks + KSWZ(r32, cb));
;     bf16x8 b1 = *reinterpret_cast<const bf16x8*>(Ks + KSWZ(32 + r32, cb));
;     p0 = __builtin_amdgcn_mfma_f32_32x32x16_bf16(b0, qr[d0], p0, 0, 0, 0);
;     p1 = __builtin_amdgcn_mfma_f32_32x32x16_bf16(b1, qr[d0], p1, 0, 0, 0); }
;   for (int d0 = 8; d0 < 12; ++d0) { int cb = (d0 * 16 + hi * 8) * 2;
;     bf16x8 b0 = *reinterpret_cast<const bf16x8*>(Ks + KSWZ(r32, cb));
;     bf16x8 b1 = *reinterpret_cast<const bf16x8*>(Ks + KSWZ(32 + r32, cb));
;     bf16x8 qf = *reinterpret_cast<const bf16x8*>(qrope + (d0 - 8) * 1024);
;     p0 = __builtin_amdgcn_mfma_f32_32x32x16_bf16(b0, qf, p0, 0, 0, 0);
;     p1 = __builtin_amdgcn_mfma_f32_32x32x16_bf16(b1, qf, p1, 0, 0, 0); }
; }
; __device__ __forceinline__ void attn_unit(const bf16_t* __restrict__ Qb, const bf16_t* __restrict__ Kh, const bf16_t* __restrict__ Vh, bf16_t* __restrict__ Ob, float* __restrict__ ssq, char* lds, LAS unsigned char* ldsl, ...
;     ...
;   unsigned kgo[3], vgo[2];
; #pragma unroll
;   for (int i = 0; i < 3; ++i) { const int P = (i * 8 + wid) * 1024 + lane * 16, row = P / 384, cp = (P % 384) >> 4, c = cp ^ ((row >> 1) & 7); kgo[i] = (unsigned)(row * 384 + c * 16); }
; #pragma unroll
;   for (int i = 0; i < 2; ++i) { const int P = (i * 8 + wid) * 1024 + lane * 16, st = P >> 9, q = (P & 511) >> 1, kk = (st >> 2) * 8 + (q >> 5), k = (kk & ~0xC) | ((kk & 4) << 1) | ((kk & 8) >> 1), c = (st & 3) * 32 + (q & 31);
;     vgo[i] = (unsigned)(k * 256 + c * 2); }
;   const int vb0 = (int)(uintptr_t)V_lds + v_rd_base(lane);
;     ...
;   constexpr int NT = SEQ / KVBLK;
;   o[0] = f32x16{}; o[1] = f32x16{}; o[2] = f32x16{}; o[3] = f32x16{};
;   f32x16 pA0, pA1, pB0, pB1; float mnA, mnB, alA, alB; bf16x8 pa0, pa1, pa2, pa3;
;   DMA_K(0, 0); DMA_V(0, 0); DMA_K(1, 1);
;   WAIT_BAR();
;   qkt(pA0, pA1, K_lds, qr, qrope, r32, hi); partialSM(pA0, pA1, m_reg, mnA, alA);
;   WAIT_BAR();
	v_mov_b32_e32 v4, v14
	v_mov_b32_e32 v5, v10
	v_pk_mul_f32 v[0:1], v[0:1], v[4:5]
	v_mov_b32_e32 v14, v11
	v_add_f32_e32 v4, v1, v0
	v_pk_mul_f32 v[0:1], v[42:43], v[32:33] op_sel_hi:[0,1]
	v_pk_mul_f32 v[0:1], v[0:1], v[6:7]
	v_mov_b32_e32 v10, v15
	v_pk_mul_f32 v[2:3], v[0:1], v[14:15]
	v_pk_mul_f32 v[0:1], v[0:1], v[10:11]
	v_pk_mul_f32 v[50:51], v[54:55], v[50:51]
	v_sub_f32_e32 v3, v2, v3
	v_add_f32_e32 v5, v1, v0
	v_cvt_pk_bf16_f32 v0, v43, v28
	v_add_f32_e32 v50, v51, v50
	v_cvt_pk_bf16_f32 v1, v25, v21
	v_cvt_pk_bf16_f32 v2, v23, v12
	v_cvt_pk_bf16_f32 v3, v9, v3
	ds_write_b128 v215, v[0:3] offset:1024
	v_cvt_pk_bf16_f32 v0, v50, v24
	v_cvt_pk_bf16_f32 v1, v20, v22
	v_cvt_pk_bf16_f32 v2, v18, v8
	v_cvt_pk_bf16_f32 v3, v4, v5
	ds_write_b128 v215, v[0:3] offset:3072
	v_mov_b32_e32 v0, v177
	s_nop 0
	global_load_lds_dwordx4 v0, s[24:25]
	v_mov_b32_e32 v0, v178
	s_mov_b32 m0, s4
	v_readfirstlane_b32 s4, v219
	global_load_lds_dwordx4 v0, s[24:25]
	v_mov_b32_e32 v0, v179
	s_mov_b32 m0, s4
	v_readfirstlane_b32 s4, v182
	global_load_lds_dwordx4 v0, s[24:25]
	v_mov_b32_e32 v0, v180
	s_mov_b32 m0, s4
	v_readfirstlane_b32 s4, v220
	global_load_lds_dwordx4 v0, s[92:93]
	v_mov_b32_e32 v0, v181
	s_mov_b32 m0, s4
	s_add_u32 s4, s24, 0x6000
	global_load_lds_dwordx4 v0, s[92:93]
	v_mov_b32_e32 v0, v177
	s_addc_u32 s5, s25, 0
	s_mov_b32 m0, s6
	v_readfirstlane_b32 s6, v221
	global_load_lds_dwordx4 v0, s[4:5]
	v_mov_b32_e32 v0, v178
	s_mov_b32 m0, s6
	v_readfirstlane_b32 s6, v222
	global_load_lds_dwordx4 v0, s[4:5]
	v_mov_b32_e32 v0, v179
	s_mov_b32 m0, s6
	s_mov_b32 s24, -2
	global_load_lds_dwordx4 v0, s[4:5]
	s_waitcnt vmcnt(0) lgkmcnt(0)
	s_barrier
	ds_read_b128 v[16:19], v198 offset:32768
	ds_read_b128 v[20:23], v198 offset:45056
	s_waitcnt lgkmcnt(0)
	v_mfma_f32_32x32x16_bf16 v[32:47], v[16:19], v[128:131], 0
	ds_read_b128 v[48:51], v199 offset:32768
	ds_read_b128 v[52:55], v199 offset:45056
	v_mov_b64_e32 v[0:1], s[48:49]
	v_mov_b64_e32 v[14:15], s[62:63]
	v_mov_b64_e32 v[2:3], s[50:51]
	v_mov_b64_e32 v[4:5], s[52:53]
	v_mov_b64_e32 v[6:7], s[54:55]
	v_mov_b64_e32 v[8:9], s[56:57]
	v_mfma_f32_32x32x16_bf16 v[16:31], v[20:23], v[128:131], 0
	v_mov_b64_e32 v[10:11], s[58:59]
	v_mov_b64_e32 v[12:13], s[60:61]
	s_waitcnt lgkmcnt(0)
	v_mfma_f32_32x32x16_bf16 v[32:47], v[48:51], v[132:135], v[32:47]
	v_mfma_f32_32x32x16_bf16 v[16:31], v[52:55], v[132:135], v[16:31]
	ds_read_b128 v[48:51], v201 offset:32768
	ds_read_b128 v[52:55], v201 offset:45056
	s_waitcnt lgkmcnt(0)
	v_mfma_f32_32x32x16_bf16 v[32:47], v[48:51], v[136:139], v[32:47]
	v_mfma_f32_32x32x16_bf16 v[16:31], v[52:55], v[136:139], v[16:31]
	ds_read_b128 v[48:51], v202 offset:32768
	ds_read_b128 v[52:55], v202 offset:45056
	s_waitcnt lgkmcnt(0)
	v_mfma_f32_32x32x16_bf16 v[32:47], v[48:51], v[156:159], v[32:47]
	v_mfma_f32_32x32x16_bf16 v[16:31], v[52:55], v[156:159], v[16:31]
	ds_read_b128 v[48:51], v203 offset:32768
	ds_read_b128 v[52:55], v203 offset:45056
	s_waitcnt lgkmcnt(0)
	v_mfma_f32_32x32x16_bf16 v[32:47], v[48:51], v[152:155], v[32:47]
	v_mfma_f32_32x32x16_bf16 v[16:31], v[52:55], v[152:155], v[16:31]
	ds_read_b128 v[48:51], v204 offset:32768
	ds_read_b128 v[52:55], v204 offset:45056
	s_waitcnt lgkmcnt(0)
	v_mfma_f32_32x32x16_bf16 v[32:47], v[48:51], v[148:151], v[32:47]
	v_mfma_f32_32x32x16_bf16 v[16:31], v[52:55], v[148:151], v[16:31]
	ds_read_b128 v[48:51], v205 offset:32768
	ds_read_b128 v[52:55], v205 offset:45056
	s_waitcnt lgkmcnt(0)
	v_mfma_f32_32x32x16_bf16 v[32:47], v[48:51], v[144:147], v[32:47]
	v_mfma_f32_32x32x16_bf16 v[16:31], v[52:55], v[144:147], v[16:31]
	ds_read_b128 v[48:51], v206 offset:32768
	ds_read_b128 v[52:55], v206 offset:45056
	s_waitcnt lgkmcnt(0)
	v_mfma_f32_32x32x16_bf16 v[32:47], v[48:51], v[140:143], v[32:47]
	v_mfma_f32_32x32x16_bf16 v[16:31], v[52:55], v[140:143], v[16:31]
	ds_read_b128 v[48:51], v207 offset:32768
	ds_read_b128 v[52:55], v207 offset:45056
	ds_read_b128 v[56:59], v215
	s_waitcnt lgkmcnt(0)
	v_mfma_f32_32x32x16_bf16 v[32:47], v[48:51], v[56:59], v[32:47]
	v_mfma_f32_32x32x16_bf16 v[16:31], v[52:55], v[56:59], v[16:31]
	ds_read_b128 v[48:51], v208 offset:32768
	ds_read_b128 v[52:55], v208 offset:45056
	ds_read_b128 v[56:59], v215 offset:1024
	s_waitcnt lgkmcnt(0)
	v_mfma_f32_32x32x16_bf16 v[32:47], v[48:51], v[56:59], v[32:47]
	v_mfma_f32_32x32x16_bf16 v[16:31], v[52:55], v[56:59], v[16:31]
	ds_read_b128 v[48:51], v209 offset:32768
	ds_read_b128 v[52:55], v209 offset:45056
	ds_read_b128 v[56:59], v215 offset:2048
	s_waitcnt lgkmcnt(0)
	v_mfma_f32_32x32x16_bf16 v[32:47], v[48:51], v[56:59], v[32:47]
	v_mfma_f32_32x32x16_bf16 v[16:31], v[52:55], v[56:59], v[16:31]
	ds_read_b128 v[48:51], v210 offset:32768
	ds_read_b128 v[52:55], v210 offset:45056
	ds_read_b128 v[56:59], v215 offset:3072
	s_waitcnt vmcnt(0) lgkmcnt(0)
	s_barrier
; #define LAS __attribute__((address_space(3)))
; __device__ __forceinline__ int v_rd_base(int lane) { return ((lane & 3) << 3) | (((lane >> 2) & 3) << 6) | (((lane >> 4) & 1) << 5) | (((lane >> 5) & 1) << 8); }
; #define WAIT_BAR() do { asm volatile("s_waitcnt vmcnt(0) lgkmcnt(0)" ::: "memory"); __builtin_amdgcn_s_barrier(); asm volatile("" ::: "memory"); } while (0)
; __device__ __forceinline__ void partialSM(f32x16& p0, f32x16& p1, float& m_reg, float& mn, float& alpha) {
;   constexpr float C = SCALE * 1.4426950408889634f;
;   float pmax = p0[0]; for (int r = 1; r < 16; ++r) pmax = fmaxf(pmax, p0[r]); for (int r = 0; r < 16; ++r) pmax = fmaxf(pmax, p1[r]);
;   { auto rr = __builtin_amdgcn_permlane32_swap(__float_as_uint(pmax), __float_as_uint(pmax), false, false);
;     pmax = fmaxf(__uint_as_float(rr[0]), __uint_as_float(rr[1])); }
;   if (__builtin_expect(__all(pmax - m_reg <= THR / SCALE), 1)) { mn = m_reg; alpha = 1.f; }
;   else { mn = fmaxf(m_reg, pmax); alpha = __builtin_amdgcn_exp2f((m_reg - mn) * C); m_reg = mn; }
;   float mnC = -mn * C;
;   for (int r = 0; r < 16; ++r) p0[r] = fmaf(p0[r], C, mnC); for (int r = 0; r < 16; ++r) p1[r] = fmaf(p1[r], C, mnC);
;   for (int r = 0; r < 16; ++r) p0[r] = __builtin_amdgcn_exp2f(p0[r]);
; }
; __device__ __forceinline__ void attn_unit(const bf16_t* __restrict__ Qb, const bf16_t* __restrict__ Kh, const bf16_t* __restrict__ Vh, bf16_t* __restrict__ Ob, float* __restrict__ ssq, char* lds, LAS unsigned char* ldsl, ...
;     ...
;   qkt(pA0, pA1, K_lds, qr, qrope, r32, hi); partialSM(pA0, pA1, m_reg, mnA, alA);
;   WAIT_BAR();
;   int kx[4];
; #pragma unroll
;   for (int jj = 0; jj < 4; ++jj) kx[jj] = r32 * 384 + ((((2 * jj + hi) ^ ((r32 >> 1) & 7))) << 4);
;   const LAS char* kl0 = (const LAS char*)(ldsl + 2 * SHM_V); const LAS char* vl0 = (const LAS char*)(ldsl + v_rd_base(lane)); const LAS char* qrl = (const LAS char*)(ldsl + SHM_QR + wid * 4096 + lane * 16);
;     ...
;   for (int j = 0; j < NT - 2; j += 2) {
;     STEP(pA0, pA1, alA, pB0, pB1, mnB, alB, j, true, true);
;     STEP(pB0, pB1, alB, pA0, pA1, mnA, alA, j + 1, true, true);
	s_waitcnt lgkmcnt(0)
	v_mfma_f32_32x32x16_bf16 v[32:47], v[48:51], v[56:59], v[32:47]
	v_mfma_f32_32x32x16_bf16 v[16:31], v[52:55], v[56:59], v[16:31]
	s_nop 10
	v_max_f32_e32 v48, v33, v33
	v_max_f32_e32 v49, v32, v32
	v_max_f32_e32 v48, v49, v48
	v_max3_f32 v48, v48, v34, v35
	v_max3_f32 v48, v48, v36, v37
	v_max3_f32 v48, v48, v38, v39
	v_max3_f32 v48, v48, v40, v41
	v_max3_f32 v48, v48, v42, v43
	v_max3_f32 v48, v48, v44, v45
	v_max3_f32 v48, v48, v46, v47
	v_max3_f32 v48, v48, v16, v17
	v_max3_f32 v48, v48, v18, v19
	v_max3_f32 v48, v48, v20, v21
	v_max3_f32 v48, v48, v22, v23
	v_max3_f32 v48, v48, v24, v25
	v_max3_f32 v48, v48, v26, v27
	v_max3_f32 v48, v48, v28, v29
	v_max3_f32 v48, v48, v30, v31
	v_mov_b32_e32 v49, v48
	s_nop 1
	v_permlane32_swap_b32_e32 v48, v49
	v_max_f32_e32 v49, v49, v49
	v_max_f32_e32 v48, v48, v48
	v_max_f32_e32 v48, v48, v49
	v_add_f32_e32 v49, 0x7149f2ca, v48
	v_cmp_ge_f32_e32 vcc, s29, v49
	s_cmp_eq_u64 vcc, exec
	s_cselect_b64 vcc, -1, 0
	v_max_f32_e32 v48, 0xf149f2ca, v48
	v_cndmask_b32_e32 v228, v48, v216, vcc
	v_sub_f32_e32 v49, 0xf149f2ca, v48
	v_mul_f32_e32 v48, 0xbdd53b94, v228
	v_mul_f32_e32 v49, 0x3dd53b94, v49
	v_fmamk_f32 v32, v32, 0x3dd53b94, v48
	v_exp_f32_e32 v80, v32
	v_exp_f32_e32 v32, v49
	v_fmamk_f32 v33, v33, 0x3dd53b94, v48
	v_fmamk_f32 v34, v34, 0x3dd53b94, v48
	v_fmamk_f32 v35, v35, 0x3dd53b94, v48
	v_fmamk_f32 v36, v36, 0x3dd53b94, v48
	v_fmamk_f32 v37, v37, 0x3dd53b94, v48
	v_fmamk_f32 v38, v38, 0x3dd53b94, v48
	v_fmamk_f32 v39, v39, 0x3dd53b94, v48
	v_fmamk_f32 v40, v40, 0x3dd53b94, v48
	v_fmamk_f32 v41, v41, 0x3dd53b94, v48
	v_fmamk_f32 v42, v42, 0x3dd53b94, v48
	v_fmamk_f32 v43, v43, 0x3dd53b94, v48
	v_fmamk_f32 v44, v44, 0x3dd53b94, v48
	v_fmamk_f32 v45, v45, 0x3dd53b94, v48
	v_fmamk_f32 v46, v46, 0x3dd53b94, v48
	v_fmamk_f32 v47, v47, 0x3dd53b94, v48
	v_exp_f32_e32 v81, v33
	v_exp_f32_e32 v82, v34
	v_exp_f32_e32 v83, v35
	v_exp_f32_e32 v84, v36
	v_exp_f32_e32 v85, v37
	v_exp_f32_e32 v86, v38
	v_exp_f32_e32 v87, v39
	v_exp_f32_e32 v88, v40
	v_exp_f32_e32 v89, v41
	v_exp_f32_e32 v90, v42
	v_exp_f32_e32 v91, v43
	v_exp_f32_e32 v92, v44
	v_exp_f32_e32 v93, v45
	v_exp_f32_e32 v94, v46
	v_exp_f32_e32 v95, v47
	v_cndmask_b32_e64 v224, v32, 1.0, vcc
	v_pk_fma_f32 v[78:79], v[30:31], s[80:81], v[48:49] op_sel_hi:[1,0,0]
	v_pk_fma_f32 v[76:77], v[28:29], s[80:81], v[48:49] op_sel_hi:[1,0,0]
	v_pk_fma_f32 v[74:75], v[26:27], s[80:81], v[48:49] op_sel_hi:[1,0,0]
	v_pk_fma_f32 v[72:73], v[24:25], s[80:81], v[48:49] op_sel_hi:[1,0,0]
	v_pk_fma_f32 v[70:71], v[22:23], s[80:81], v[48:49] op_sel_hi:[1,0,0]
	v_pk_fma_f32 v[68:69], v[20:21], s[80:81], v[48:49] op_sel_hi:[1,0,0]
	v_pk_fma_f32 v[66:67], v[18:19], s[80:81], v[48:49] op_sel_hi:[1,0,0]
	v_pk_fma_f32 v[64:65], v[16:17], s[80:81], v[48:49] op_sel_hi:[1,0,0]
	v_mov_b64_e32 v[62:63], v[14:15]
	v_mov_b64_e32 v[46:47], v[14:15]
	v_mov_b64_e32 v[30:31], v[14:15]
	v_mov_b64_e32 v[60:61], v[12:13]
	v_mov_b64_e32 v[58:59], v[10:11]
	v_mov_b64_e32 v[56:57], v[8:9]
	v_mov_b64_e32 v[54:55], v[6:7]
	v_mov_b64_e32 v[52:53], v[4:5]
	v_mov_b64_e32 v[50:51], v[2:3]
	v_mov_b64_e32 v[48:49], v[0:1]
	v_mov_b64_e32 v[44:45], v[12:13]
	v_mov_b64_e32 v[42:43], v[10:11]
	v_mov_b64_e32 v[40:41], v[8:9]
	v_mov_b64_e32 v[38:39], v[6:7]
	v_mov_b64_e32 v[36:37], v[4:5]
	v_mov_b64_e32 v[34:35], v[2:3]
	v_mov_b64_e32 v[32:33], v[0:1]
	v_mov_b64_e32 v[28:29], v[12:13]
	v_mov_b64_e32 v[26:27], v[10:11]
	v_mov_b64_e32 v[24:25], v[8:9]
	v_mov_b64_e32 v[22:23], v[6:7]
	v_mov_b64_e32 v[20:21], v[4:5]
	v_mov_b64_e32 v[18:19], v[2:3]
	v_mov_b64_e32 v[16:17], v[0:1]
	v_add_u32_e32 v225, 0x4000, v182
	v_add_u32_e32 v226, 0x6000, v182
	ds_read_b128 v[230:233], v186 offset:57344
	ds_read_b128 v[234:237], v187 offset:12288
.LBB0_1011:
	s_add_u32 s4, s12, s31
	s_addc_u32 s5, s13, s9
	s_add_u32 s4, s4, 0x1dd0c000
	s_addc_u32 s5, s5, 0
	s_add_u32 s6, s12, s90
	s_addc_u32 s7, s13, s91
	s_add_u32 s6, s6, 0x25504000
	s_addc_u32 s7, s7, 0
	s_waitcnt lgkmcnt(0)
	ds_read_b128 v[244:247], v186 offset:57600
	ds_read_b128 v[248:251], v187 offset:12544
	ds_read_b128 v[238:241], v215
	v_exp_f32_e32 v64, v64
	v_exp_f32_e32 v65, v65
	v_mfma_f32_32x32x16_bf16 v[112:127], v[230:233], v[128:131], 0
	v_add_f32_e32 v96, 0, v80
	v_add_f32_e32 v162, v81, v96
	s_add_i32 m0, s98, 0x8000
	v_mfma_f32_32x32x16_bf16 v[96:111], v[234:237], v[128:131], 0
	global_load_lds_dwordx4 v177, s[4:5]
	s_waitcnt lgkmcnt(0)
	ds_read_b128 v[230:233], v188 offset:57344
	ds_read_b128 v[234:237], v189 offset:12288
	v_add_f32_e32 v162, v82, v162
	v_add_f32_e32 v162, v83, v162
	v_add_f32_e32 v162, v64, v162
	v_mfma_f32_32x32x16_bf16 v[112:127], v[244:247], v[238:241], v[112:127]
	v_exp_f32_e32 v66, v66
	v_exp_f32_e32 v67, v67
	v_add_f32_e32 v162, v65, v162
	s_add_i32 m0, s98, 0xa000
	v_mfma_f32_32x32x16_bf16 v[96:111], v[248:251], v[238:241], v[96:111]
	global_load_lds_dwordx4 v178, s[4:5]
	s_waitcnt lgkmcnt(0)
	ds_read_b128 v[244:247], v188 offset:57600
	ds_read_b128 v[248:251], v189 offset:12544
	ds_read_b128 v[238:241], v215 offset:1024
	v_add_f32_e32 v162, v84, v162
	v_add_f32_e32 v162, v85, v162
	v_add_f32_e32 v162, v66, v162
	v_mfma_f32_32x32x16_bf16 v[112:127], v[230:233], v[132:135], v[112:127]
	v_exp_f32_e32 v68, v68
	v_exp_f32_e32 v69, v69
	v_add_f32_e32 v162, v67, v162
	s_add_i32 m0, s98, 0xc000
	v_mfma_f32_32x32x16_bf16 v[96:111], v[234:237], v[132:135], v[96:111]
	global_load_lds_dwordx4 v179, s[4:5]
	s_waitcnt lgkmcnt(0)
; template <int S> __device__ __forceinline__ void fsm_chunk(f32x16& c0, f32x16& c1, float& ps, bf16x8& pa0, bf16x8& pa1, bf16x8& pa2, bf16x8& pa3) {
;   if constexpr (S < 8) { c1[2 * S] = __builtin_amdgcn_exp2f(c1[2 * S]); c1[2 * S + 1] = __builtin_amdgcn_exp2f(c1[2 * S + 1]); ps += c0[2 * S]; ps += c0[2 * S + 1]; if constexpr (S > 0) { ps += c1[2 * S - 2]; ps += c1[2 * S - 1]; } asm volatile("" : "+v"(c1), "+v"(ps)); }
;   else if constexpr (S == 8) { ps += c1[14]; ps += c1[15]; PK4(c0, 0, pa0); asm volatile("" : "+v"(pa0), "+v"(ps)); }
;   else if constexpr (S == 9) { PK4(c0, 8, pa1); asm volatile("" : "+v"(pa1)); }
;   else if constexpr (S == 10) { PK4(c1, 0, pa2); asm volatile("" : "+v"(pa2)); }
;   else { PK4(c1, 8, pa3); asm volatile("" : "+v"(pa3)); }
; }
; __device__ __forceinline__ void qk_fsm(f32x16& n0, f32x16& n1, f32x16& c0, f32x16& c1, float alC, float& l_reg, bf16x8& pa0, bf16x8& pa1, bf16x8& pa2, bf16x8& pa3,
;                                        const LAS char* kl, const int (&kx)[4], const bf16x8* qr, const LAS char* qrl) {
;   float ps = 0.f;
;     ...
;   QSLOT(0) QSLOT(1) QSLOT(2) QSLOT(3) QSLOT(4) QSLOT(5) QSLOT(6) QSLOT(7) QSLOT(8) QSLOT(9) QSLOT(10) QSLOT(11)
;     ...
;   { auto rr = __builtin_amdgcn_permlane32_swap(__float_as_uint(ps), __float_as_uint(ps), false, false); ps = __uint_as_float(rr[0]) + __uint_as_float(rr[1]); }
;   l_reg = l_reg * alC + ps;
; }
; template <int S> __device__ __forceinline__ void psm_chunk(f32x16& p0, f32x16& p1, float& mx, float& m_reg, float& alpha, float& mnC) {
;   constexpr float C = SCALE * 1.4426950408889634f; const float Cv = C;
;   if constexpr (S == 0) { mx = p0[0];
; #pragma unroll
;     for (int r = 1; r < 16; ++r) mx = fmaxf(mx, p0[r]); }
;   else if constexpr (S == 1) {
; #pragma unroll
;     for (int r = 0; r < 16; ++r) mx = fmaxf(mx, p1[r]);
;     { auto rr = __builtin_amdgcn_permlane32_swap(__float_as_uint(mx), __float_as_uint(mx), false, false); mx = fmaxf(__uint_as_float(rr[0]), __uint_as_float(rr[1])); }
;     const float mn = (mx - m_reg > THR / SCALE) ? fmaxf(m_reg, mx) : m_reg; alpha = __builtin_amdgcn_exp2f((m_reg - mn) * C); m_reg = mn; mnC = -mn * C; }
;   else if constexpr (S == 2) {
; #pragma unroll
;     for (int r = 0; r < 8; ++r) p0[r] = fma_s(p0[r], Cv, mnC); }
;   else if constexpr (S == 3) {
; #pragma unroll
;     for (int r = 8; r < 16; ++r) p0[r] = fma_s(p0[r], Cv, mnC);
	ds_read_b128 v[230:233], v190 offset:57344
	ds_read_b128 v[234:237], v191 offset:12288
	v_add_f32_e32 v162, v86, v162
	v_add_f32_e32 v162, v87, v162
	v_add_f32_e32 v162, v68, v162
	v_mfma_f32_32x32x16_bf16 v[112:127], v[244:247], v[238:241], v[112:127]
	v_exp_f32_e32 v70, v70
	v_exp_f32_e32 v71, v71
	v_add_f32_e32 v162, v69, v162
	s_add_i32 m0, s98, 0x4000
	v_mfma_f32_32x32x16_bf16 v[96:111], v[248:251], v[238:241], v[96:111]
	global_load_lds_dwordx4 v180, s[6:7]
	s_waitcnt lgkmcnt(0)
	ds_read_b128 v[244:247], v190 offset:57600
	ds_read_b128 v[248:251], v191 offset:12544
	ds_read_b128 v[238:241], v215 offset:2048
	v_add_f32_e32 v162, v88, v162
	v_add_f32_e32 v162, v89, v162
	v_add_f32_e32 v162, v70, v162
	v_mfma_f32_32x32x16_bf16 v[112:127], v[230:233], v[136:139], v[112:127]
	v_exp_f32_e32 v72, v72
	v_exp_f32_e32 v73, v73
	v_add_f32_e32 v162, v71, v162
	s_add_i32 m0, s98, 0x6000
	v_mfma_f32_32x32x16_bf16 v[96:111], v[234:237], v[136:139], v[96:111]
	global_load_lds_dwordx4 v181, s[6:7]
	s_waitcnt lgkmcnt(0)
	ds_read_b128 v[230:233], v192 offset:57344
	ds_read_b128 v[234:237], v193 offset:12288
	v_add_f32_e32 v162, v90, v162
	v_add_f32_e32 v162, v91, v162
	v_add_f32_e32 v162, v72, v162
	v_mfma_f32_32x32x16_bf16 v[112:127], v[244:247], v[238:241], v[112:127]
	v_exp_f32_e32 v74, v74
	v_exp_f32_e32 v75, v75
	v_add_f32_e32 v162, v73, v162
	v_mfma_f32_32x32x16_bf16 v[96:111], v[248:251], v[238:241], v[96:111]
	s_waitcnt lgkmcnt(0)
	ds_read_b128 v[244:247], v192 offset:57600
	ds_read_b128 v[248:251], v193 offset:12544
	ds_read_b128 v[238:241], v215 offset:3072
	v_add_f32_e32 v162, v92, v162
	v_add_f32_e32 v162, v93, v162
	v_add_f32_e32 v162, v74, v162
	v_mfma_f32_32x32x16_bf16 v[112:127], v[230:233], v[156:159], v[112:127]
	v_exp_f32_e32 v76, v76
	v_exp_f32_e32 v77, v77
	v_add_f32_e32 v162, v75, v162
	v_mfma_f32_32x32x16_bf16 v[96:111], v[234:237], v[156:159], v[96:111]
	s_waitcnt lgkmcnt(0)
	ds_read_b128 v[230:233], v186 offset:57472
	ds_read_b128 v[234:237], v187 offset:12416
	v_add_f32_e32 v162, v94, v162
	v_add_f32_e32 v162, v95, v162
	v_add_f32_e32 v162, v76, v162
	v_mfma_f32_32x32x16_bf16 v[112:127], v[244:247], v[238:241], v[112:127]
	v_exp_f32_e32 v78, v78
	v_exp_f32_e32 v79, v79
	v_add_f32_e32 v162, v77, v162
	v_mfma_f32_32x32x16_bf16 v[96:111], v[248:251], v[238:241], v[96:111]
	s_waitcnt lgkmcnt(0)
	ds_read_b128 v[244:247], v188 offset:57472
	ds_read_b128 v[248:251], v189 offset:12416
	v_add_f32_e32 v162, v162, v78
	v_cvt_pk_bf16_f32 v80, v80, v81
	v_cvt_pk_bf16_f32 v81, v82, v83
	v_cvt_pk_bf16_f32 v82, v84, v85
	v_mfma_f32_32x32x16_bf16 v[112:127], v[230:233], v[152:155], v[112:127]
	v_cvt_pk_bf16_f32 v83, v86, v87
	v_add_f32_e32 v227, v79, v162
	v_permlane32_swap_b32_e32 v80, v82
	v_permlane32_swap_b32_e32 v81, v83
	v_mfma_f32_32x32x16_bf16 v[96:111], v[234:237], v[152:155], v[96:111]
	s_waitcnt lgkmcnt(0)
	ds_read_b128 v[230:233], v190 offset:57472
	ds_read_b128 v[234:237], v191 offset:12416
	v_cvt_pk_bf16_f32 v84, v88, v89
	v_cvt_pk_bf16_f32 v85, v90, v91
	v_cvt_pk_bf16_f32 v86, v92, v93
	v_mfma_f32_32x32x16_bf16 v[112:127], v[244:247], v[148:151], v[112:127]
	v_cvt_pk_bf16_f32 v87, v94, v95
	v_permlane32_swap_b32_e32 v84, v86
	v_mfma_f32_32x32x16_bf16 v[96:111], v[248:251], v[148:151], v[96:111]
	v_permlane32_swap_b32_e32 v85, v87
	s_waitcnt lgkmcnt(0)
	ds_read_b128 v[244:247], v192 offset:57472
	ds_read_b128 v[248:251], v193 offset:12416
	v_cvt_pk_bf16_f32 v64, v64, v65
	v_cvt_pk_bf16_f32 v65, v66, v67
	v_cvt_pk_bf16_f32 v66, v68, v69
	v_mfma_f32_32x32x16_bf16 v[112:127], v[230:233], v[144:147], v[112:127]
	v_cvt_pk_bf16_f32 v67, v70, v71
	v_permlane32_swap_b32_e32 v64, v66
	v_mfma_f32_32x32x16_bf16 v[96:111], v[234:237], v[144:147], v[96:111]
	v_permlane32_swap_b32_e32 v65, v67
	s_waitcnt lgkmcnt(0)
	ds_read_b64_tr_b16 v[234:235], v184
	ds_read_b64_tr_b16 v[236:237], v184 offset:2048
	ds_read_b64_tr_b16 v[238:239], v184 offset:4096
	ds_read_b64_tr_b16 v[240:241], v184 offset:6144
	v_cvt_pk_bf16_f32 v68, v72, v73
	v_cvt_pk_bf16_f32 v69, v74, v75
	v_cvt_pk_bf16_f32 v70, v76, v77
	v_mfma_f32_32x32x16_bf16 v[112:127], v[244:247], v[140:143], v[112:127]
	v_cvt_pk_bf16_f32 v71, v78, v79
	v_permlane32_swap_b32_e32 v68, v70
	v_mfma_f32_32x32x16_bf16 v[96:111], v[248:251], v[140:143], v[96:111]
	v_permlane32_swap_b32_e32 v69, v71
	v_mov_b32_e32 v229, v227
	s_nop 1
	v_permlane32_swap_b32_e32 v227, v229
	s_waitcnt lgkmcnt(0)
	ds_read_b64_tr_b16 v[72:73], v184 offset:8192
	ds_read_b64_tr_b16 v[74:75], v184 offset:10240
	ds_read_b64_tr_b16 v[76:77], v184 offset:12288
	ds_read_b64_tr_b16 v[78:79], v184 offset:14336
	v_max_f32_e32 v88, v113, v113
	v_max_f32_e32 v89, v112, v112
	v_mfma_f32_32x32x16_bf16 v[0:15], v[80:83], v[234:237], v[0:15]
	v_max_f32_e32 v88, v89, v88
	v_max3_f32 v88, v88, v114, v115
	v_max3_f32 v88, v88, v116, v117
	v_max3_f32 v252, v88, v118, v119
	v_max3_f32 v252, v252, v120, v121
	v_max3_f32 v252, v252, v122, v123
	v_max3_f32 v252, v252, v124, v125
	v_mfma_f32_32x32x16_bf16 v[0:15], v[84:87], v[238:241], v[0:15]
	v_max3_f32 v88, v252, v126, v127
	s_waitcnt lgkmcnt(0)
	ds_read_b64_tr_b16 v[234:235], v184 offset:512
	ds_read_b64_tr_b16 v[236:237], v184 offset:2560
	ds_read_b64_tr_b16 v[238:239], v184 offset:4608
	ds_read_b64_tr_b16 v[240:241], v184 offset:6656
	v_max3_f32 v88, v88, v96, v97
	v_max3_f32 v88, v88, v98, v99
	v_max3_f32 v88, v88, v100, v101
	v_max3_f32 v88, v88, v102, v103
	v_mfma_f32_32x32x16_bf16 v[0:15], v[64:67], v[72:75], v[0:15]
	v_max3_f32 v88, v88, v104, v105
	v_max3_f32 v88, v88, v106, v107
	v_max3_f32 v88, v88, v108, v109
	v_max3_f32 v88, v88, v110, v111
	v_mov_b32_e32 v89, v88
	s_nop 1
	v_permlane32_swap_b32_e32 v88, v89
	v_max_f32_e32 v89, v89, v89
	v_max_f32_e32 v88, v88, v88
	v_max_f32_e32 v88, v88, v89
	v_mfma_f32_32x32x16_bf16 v[0:15], v[68:71], v[76:79], v[0:15]
	v_sub_f32_e32 v89, v88, v228
	v_cmp_lt_f32_e32 vcc, s29, v89
	v_max_f32_e32 v89, v228, v228
	v_max_f32_e32 v89, v89, v88
	v_cndmask_b32_e32 v230, v228, v89, vcc
	v_sub_f32_e32 v89, v228, v230
	v_mul_f32_e32 v89, 0x3dd53b94, v89
	v_exp_f32_e32 v223, v89
	v_mul_f32_e32 v89, 0xbdd53b94, v230
	s_waitcnt lgkmcnt(0)
; #define LAS __attribute__((address_space(3)))
; template <int S> __device__ __forceinline__ void psm_chunk(f32x16& p0, f32x16& p1, float& mx, float& m_reg, float& alpha, float& mnC) {
;   constexpr float C = SCALE * 1.4426950408889634f; const float Cv = C;
;   if constexpr (S == 0) { mx = p0[0];
; #pragma unroll
;     for (int r = 1; r < 16; ++r) mx = fmaxf(mx, p0[r]); }
;   else if constexpr (S == 1) {
; #pragma unroll
;     for (int r = 0; r < 16; ++r) mx = fmaxf(mx, p1[r]);
;     { auto rr = __builtin_amdgcn_permlane32_swap(__float_as_uint(mx), __float_as_uint(mx), false, false); mx = fmaxf(__uint_as_float(rr[0]), __uint_as_float(rr[1])); }
;     const float mn = (mx - m_reg > THR / SCALE) ? fmaxf(m_reg, mx) : m_reg; alpha = __builtin_amdgcn_exp2f((m_reg - mn) * C); m_reg = mn; mnC = -mn * C; }
;   else if constexpr (S == 2) {
; #pragma unroll
;     for (int r = 0; r < 8; ++r) p0[r] = fma_s(p0[r], Cv, mnC); }
;   else if constexpr (S == 3) {
; #pragma unroll
;     for (int r = 8; r < 16; ++r) p0[r] = fma_s(p0[r], Cv, mnC);
; #pragma unroll
;     for (int r = 0; r < 4; ++r) p0[r] = __builtin_amdgcn_exp2f(p0[r]); }
;   else if constexpr (S == 4) {
; #pragma unroll
;     for (int r = 0; r < 8; ++r) p1[r] = fma_s(p1[r], Cv, mnC);
; #pragma unroll
;     for (int r = 4; r < 8; ++r) p0[r] = __builtin_amdgcn_exp2f(p0[r]); }
;   else if constexpr (S == 5) {
; #pragma unroll
;     for (int r = 8; r < 16; ++r) p1[r] = fma_s(p1[r], Cv, mnC);
; #pragma unroll
;     for (int r = 8; r < 12; ++r) p0[r] = __builtin_amdgcn_exp2f(p0[r]); }
;   else if constexpr (S == 6) {
; #pragma unroll
;     for (int r = 12; r < 16; ++r) p0[r] = __builtin_amdgcn_exp2f(p0[r]); }
;   if constexpr (S == 0 || S == 1) asm volatile("" : "+v"(mx), "+v"(alpha), "+v"(mnC), "+v"(m_reg));
;   else if constexpr (S < 7) asm volatile("" : "+v"(p0), "+v"(p1));
; }
; __device__ __forceinline__ void pv_psm(f32x16* o, const LAS char* vl, bf16x8 pa0, bf16x8 pa1, bf16x8 pa2, bf16x8 pa3, f32x16& n0, f32x16& n1, float& m_reg, float& alN) {
;   float mx = 0.f, mnC = 0.f;
;     ...
;   VSLOT(0) VSLOT(1) VSLOT(2) VSLOT(3) VSLOT(4) VSLOT(5) VSLOT(6) VSLOT(7)
; __device__ __forceinline__ void attn_unit(const bf16_t* __restrict__ Qb, const bf16_t* __restrict__ Kh, const bf16_t* __restrict__ Vh, bf16_t* __restrict__ Ob, float* __restrict__ ssq, char* lds, LAS unsigned char* ldsl, ...
;     ...
;   constexpr int NT = SEQ / KVBLK;
	ds_read_b64_tr_b16 v[72:73], v184 offset:8704
	ds_read_b64_tr_b16 v[74:75], v184 offset:10752
	ds_read_b64_tr_b16 v[76:77], v184 offset:12800
	ds_read_b64_tr_b16 v[78:79], v184 offset:14848
	v_fma_f32 v112, v112, v211, v89
	v_fma_f32 v113, v113, v211, v89
	v_mfma_f32_32x32x16_bf16 v[48:63], v[80:83], v[234:237], v[48:63]
	v_fma_f32 v114, v114, v211, v89
	v_fma_f32 v115, v115, v211, v89
	v_fma_f32 v116, v116, v211, v89
	v_fma_f32 v117, v117, v211, v89
	v_fma_f32 v118, v118, v211, v89
	v_fma_f32 v119, v119, v211, v89
	v_mfma_f32_32x32x16_bf16 v[48:63], v[84:87], v[238:241], v[48:63]
	s_waitcnt lgkmcnt(0)
	ds_read_b64_tr_b16 v[234:235], v184 offset:1024
	ds_read_b64_tr_b16 v[236:237], v184 offset:3072
	ds_read_b64_tr_b16 v[238:239], v184 offset:5120
	ds_read_b64_tr_b16 v[240:241], v184 offset:7168
	v_fma_f32 v120, v120, v211, v89
	v_fma_f32 v121, v121, v211, v89
	v_mfma_f32_32x32x16_bf16 v[48:63], v[64:67], v[72:75], v[48:63]
	v_fma_f32 v122, v122, v211, v89
	v_fma_f32 v123, v123, v211, v89
	v_fma_f32 v124, v124, v211, v89
	v_exp_f32_e32 v112, v112
	v_exp_f32_e32 v113, v113
	v_exp_f32_e32 v114, v114
	v_exp_f32_e32 v115, v115
	v_mfma_f32_32x32x16_bf16 v[48:63], v[68:71], v[76:79], v[48:63]
	v_fma_f32 v125, v125, v211, v89
	v_fma_f32 v126, v126, v211, v89
	v_fma_f32 v127, v127, v211, v89
	s_nop 0
	s_waitcnt lgkmcnt(0)
	ds_read_b64_tr_b16 v[72:73], v184 offset:9216
	ds_read_b64_tr_b16 v[74:75], v184 offset:11264
	ds_read_b64_tr_b16 v[76:77], v184 offset:13312
	ds_read_b64_tr_b16 v[78:79], v184 offset:15360
	v_fma_f32 v96, v96, v211, v89
	v_fma_f32 v97, v97, v211, v89
	v_mfma_f32_32x32x16_bf16 v[32:47], v[80:83], v[234:237], v[32:47]
	v_fma_f32 v98, v98, v211, v89
	v_fma_f32 v99, v99, v211, v89
	v_fma_f32 v100, v100, v211, v89
	v_exp_f32_e32 v116, v116
	v_exp_f32_e32 v117, v117
	v_exp_f32_e32 v118, v118
	v_exp_f32_e32 v119, v119
	v_mfma_f32_32x32x16_bf16 v[32:47], v[84:87], v[238:241], v[32:47]
	v_fma_f32 v101, v101, v211, v89
	v_fma_f32 v102, v102, v211, v89
	v_fma_f32 v103, v103, v211, v89
	s_nop 0
	s_waitcnt lgkmcnt(0)
	ds_read_b64_tr_b16 v[234:235], v184 offset:1536
	ds_read_b64_tr_b16 v[236:237], v184 offset:3584
	ds_read_b64_tr_b16 v[238:239], v184 offset:5632
	ds_read_b64_tr_b16 v[240:241], v184 offset:7680
	v_fma_f32 v104, v104, v211, v89
	v_fma_f32 v105, v105, v211, v89
	v_mfma_f32_32x32x16_bf16 v[32:47], v[64:67], v[72:75], v[32:47]
	v_fma_f32 v106, v106, v211, v89
	v_fma_f32 v107, v107, v211, v89
	v_fma_f32 v108, v108, v211, v89
	v_exp_f32_e32 v120, v120
	v_exp_f32_e32 v121, v121
	v_exp_f32_e32 v122, v122
	v_exp_f32_e32 v123, v123
	v_mfma_f32_32x32x16_bf16 v[32:47], v[68:71], v[76:79], v[32:47]
	v_fma_f32 v109, v109, v211, v89
	v_fma_f32 v110, v110, v211, v89
	v_fma_f32 v111, v111, v211, v89
	s_nop 0
	s_waitcnt lgkmcnt(0)
	ds_read_b64_tr_b16 v[72:73], v184 offset:9728
	ds_read_b64_tr_b16 v[74:75], v184 offset:11776
	ds_read_b64_tr_b16 v[76:77], v184 offset:13824
	ds_read_b64_tr_b16 v[78:79], v184 offset:15872
	v_exp_f32_e32 v124, v124
	v_exp_f32_e32 v125, v125
	v_mfma_f32_32x32x16_bf16 v[16:31], v[80:83], v[234:237], v[16:31]
	v_exp_f32_e32 v126, v126
	v_exp_f32_e32 v127, v127
	v_mfma_f32_32x32x16_bf16 v[16:31], v[84:87], v[238:241], v[16:31]
	s_waitcnt lgkmcnt(0)
	v_cmp_gt_f32_e32 vcc, 1.0, v223
	s_waitcnt vmcnt(0) lgkmcnt(0)
	s_barrier
	ds_read_b128 v[232:235], v186 offset:32768
	ds_read_b128 v[236:239], v186 offset:45056
	v_mfma_f32_32x32x16_bf16 v[16:31], v[64:67], v[72:75], v[16:31]
	v_mfma_f32_32x32x16_bf16 v[16:31], v[68:71], v[76:79], v[16:31]
	s_cbranch_vccz .LBB0_1015
	s_and_saveexec_b64 s[6:7], s[40:41]
	ds_write_b32 v185, v223 offset:128
	s_or_b64 exec, exec, s[6:7]
	s_waitcnt lgkmcnt(0)
	ds_read_b128 v[64:67], v196 offset:224
	ds_read_b128 v[68:71], v196 offset:192
	ds_read_b128 v[72:75], v196 offset:160
	ds_read_b128 v[76:79], v196 offset:128
	s_waitcnt lgkmcnt(0)
	v_pk_mul_f32 v[12:13], v[12:13], v[64:65]
	v_pk_mul_f32 v[8:9], v[8:9], v[68:69]
	v_pk_mul_f32 v[4:5], v[4:5], v[72:73]
	v_pk_mul_f32 v[14:15], v[14:15], v[66:67]
	v_pk_mul_f32 v[10:11], v[10:11], v[70:71]
	v_pk_mul_f32 v[6:7], v[6:7], v[74:75]
	v_pk_mul_f32 v[2:3], v[2:3], v[78:79]
	v_pk_mul_f32 v[0:1], v[0:1], v[76:77]
	v_pk_mul_f32 v[60:61], v[60:61], v[64:65]
	v_pk_mul_f32 v[56:57], v[56:57], v[68:69]
	v_pk_mul_f32 v[52:53], v[52:53], v[72:73]
	v_pk_mul_f32 v[62:63], v[62:63], v[66:67]
	v_pk_mul_f32 v[58:59], v[58:59], v[70:71]
	v_pk_mul_f32 v[54:55], v[54:55], v[74:75]
	v_pk_mul_f32 v[50:51], v[50:51], v[78:79]
	v_pk_mul_f32 v[48:49], v[48:49], v[76:77]
	v_pk_mul_f32 v[44:45], v[44:45], v[64:65]
	v_pk_mul_f32 v[40:41], v[40:41], v[68:69]
	v_pk_mul_f32 v[36:37], v[36:37], v[72:73]
	v_pk_mul_f32 v[46:47], v[46:47], v[66:67]
	v_pk_mul_f32 v[42:43], v[42:43], v[70:71]
	v_pk_mul_f32 v[38:39], v[38:39], v[74:75]
	v_pk_mul_f32 v[34:35], v[34:35], v[78:79]
	v_pk_mul_f32 v[32:33], v[32:33], v[76:77]
	v_pk_mul_f32 v[28:29], v[28:29], v[64:65]
	v_pk_mul_f32 v[24:25], v[24:25], v[68:69]
	v_pk_mul_f32 v[20:21], v[20:21], v[72:73]
	v_pk_mul_f32 v[30:31], v[30:31], v[66:67]
	v_pk_mul_f32 v[26:27], v[26:27], v[70:71]
	v_pk_mul_f32 v[22:23], v[22:23], v[74:75]
	v_pk_mul_f32 v[18:19], v[18:19], v[78:79]
	v_pk_mul_f32 v[16:17], v[16:17], v[76:77]
; #define LAS __attribute__((address_space(3)))
; __device__ __forceinline__ void qk_fsm(f32x16& n0, f32x16& n1, f32x16& c0, f32x16& c1, float alC, float& l_reg, bf16x8& pa0, bf16x8& pa1, bf16x8& pa2, bf16x8& pa3,
;                                        const LAS char* kl, const int (&kx)[4], const bf16x8* qr, const LAS char* qrl) {
;   float ps = 0.f;
;     ...
;   QSLOT(0) QSLOT(1) QSLOT(2) QSLOT(3) QSLOT(4) QSLOT(5) QSLOT(6) QSLOT(7) QSLOT(8) QSLOT(9) QSLOT(10) QSLOT(11)
;     ...
;   { auto rr = __builtin_amdgcn_permlane32_swap(__float_as_uint(ps), __float_as_uint(ps), false, false); ps = __uint_as_float(rr[0]) + __uint_as_float(rr[1]); }
;   l_reg = l_reg * alC + ps;
; }
.LBB0_1015:
	s_add_u32 s4, s12, s31
	s_addc_u32 s5, s13, s9
	s_add_u32 s4, s4, 0x1dd12000
	s_addc_u32 s5, s5, 0
	s_add_u32 s6, s12, s90
	s_addc_u32 s7, s13, s91
	s_add_u32 s6, s6, 0x25508000
	s_addc_u32 s7, s7, 0
	s_waitcnt lgkmcnt(0)
	ds_read_b128 v[244:247], v186 offset:33024
	ds_read_b128 v[248:251], v186 offset:45312
	ds_read_b128 v[240:243], v215
	v_exp_f32_e32 v96, v96
	v_exp_f32_e32 v97, v97
	v_mfma_f32_32x32x16_bf16 v[80:95], v[232:235], v[128:131], 0
	v_add_f32_e32 v64, 0, v112
	v_add_f32_e32 v162, v113, v64
	s_add_i32 m0, s98, 0xe000
	v_mfma_f32_32x32x16_bf16 v[64:79], v[236:239], v[128:131], 0
	global_load_lds_dwordx4 v177, s[4:5]
	s_waitcnt lgkmcnt(0)
	ds_read_b128 v[232:235], v188 offset:32768
	ds_read_b128 v[236:239], v188 offset:45056
	v_add_f32_e32 v162, v114, v162
	v_add_f32_e32 v162, v115, v162
	v_add_f32_e32 v162, v96, v162
	v_mfma_f32_32x32x16_bf16 v[80:95], v[244:247], v[240:243], v[80:95]
	v_exp_f32_e32 v98, v98
	v_exp_f32_e32 v99, v99
	v_add_f32_e32 v162, v97, v162
	s_add_i32 m0, s98, 0x10000
	v_mfma_f32_32x32x16_bf16 v[64:79], v[248:251], v[240:243], v[64:79]
	global_load_lds_dwordx4 v178, s[4:5]
	s_waitcnt lgkmcnt(0)
	ds_read_b128 v[244:247], v188 offset:33024
	ds_read_b128 v[248:251], v188 offset:45312
	ds_read_b128 v[240:243], v215 offset:1024
	v_add_f32_e32 v162, v116, v162
	v_add_f32_e32 v162, v117, v162
	v_add_f32_e32 v162, v98, v162
	v_mfma_f32_32x32x16_bf16 v[80:95], v[232:235], v[132:135], v[80:95]
	v_exp_f32_e32 v100, v100
	v_exp_f32_e32 v101, v101
	v_add_f32_e32 v162, v99, v162
	s_add_i32 m0, s98, 0x12000
	v_mfma_f32_32x32x16_bf16 v[64:79], v[236:239], v[132:135], v[64:79]
	global_load_lds_dwordx4 v179, s[4:5]
	s_waitcnt lgkmcnt(0)
	ds_read_b128 v[232:235], v190 offset:32768
	ds_read_b128 v[236:239], v190 offset:45056
	v_add_f32_e32 v162, v118, v162
	v_add_f32_e32 v162, v119, v162
	v_add_f32_e32 v162, v100, v162
	v_mfma_f32_32x32x16_bf16 v[80:95], v[244:247], v[240:243], v[80:95]
	v_exp_f32_e32 v102, v102
	v_exp_f32_e32 v103, v103
	v_add_f32_e32 v162, v101, v162
	s_mov_b32 m0, s98
	v_mfma_f32_32x32x16_bf16 v[64:79], v[248:251], v[240:243], v[64:79]
	global_load_lds_dwordx4 v180, s[6:7]
	s_waitcnt lgkmcnt(0)
	ds_read_b128 v[244:247], v190 offset:33024
	ds_read_b128 v[248:251], v190 offset:45312
	ds_read_b128 v[240:243], v215 offset:2048
	v_add_f32_e32 v162, v120, v162
	v_add_f32_e32 v162, v121, v162
	v_add_f32_e32 v162, v102, v162
	v_mfma_f32_32x32x16_bf16 v[80:95], v[232:235], v[136:139], v[80:95]
	v_exp_f32_e32 v104, v104
	v_exp_f32_e32 v105, v105
	v_add_f32_e32 v162, v103, v162
	s_add_i32 m0, s98, 0x2000
	v_mfma_f32_32x32x16_bf16 v[64:79], v[236:239], v[136:139], v[64:79]
	global_load_lds_dwordx4 v181, s[6:7]
	s_waitcnt lgkmcnt(0)
	ds_read_b128 v[232:235], v192 offset:32768
	ds_read_b128 v[236:239], v192 offset:45056
	v_add_f32_e32 v162, v122, v162
	v_add_f32_e32 v162, v123, v162
	v_add_f32_e32 v162, v104, v162
	v_mfma_f32_32x32x16_bf16 v[80:95], v[244:247], v[240:243], v[80:95]
	v_exp_f32_e32 v106, v106
	v_exp_f32_e32 v107, v107
	v_add_f32_e32 v162, v105, v162
	v_mfma_f32_32x32x16_bf16 v[64:79], v[248:251], v[240:243], v[64:79]
	s_waitcnt lgkmcnt(0)
	ds_read_b128 v[244:247], v192 offset:33024
	ds_read_b128 v[248:251], v192 offset:45312
	ds_read_b128 v[240:243], v215 offset:3072
	v_add_f32_e32 v162, v124, v162
	v_add_f32_e32 v162, v125, v162
	v_add_f32_e32 v162, v106, v162
	v_mfma_f32_32x32x16_bf16 v[80:95], v[232:235], v[156:159], v[80:95]
	v_exp_f32_e32 v108, v108
	v_exp_f32_e32 v109, v109
	v_add_f32_e32 v162, v107, v162
	v_mfma_f32_32x32x16_bf16 v[64:79], v[236:239], v[156:159], v[64:79]
	s_waitcnt lgkmcnt(0)
	ds_read_b128 v[232:235], v186 offset:32896
	ds_read_b128 v[236:239], v186 offset:45184
	v_add_f32_e32 v162, v126, v162
	v_add_f32_e32 v162, v127, v162
	v_add_f32_e32 v162, v108, v162
	v_mfma_f32_32x32x16_bf16 v[80:95], v[244:247], v[240:243], v[80:95]
	v_exp_f32_e32 v110, v110
	v_exp_f32_e32 v111, v111
	v_add_f32_e32 v162, v109, v162
	v_mfma_f32_32x32x16_bf16 v[64:79], v[248:251], v[240:243], v[64:79]
	s_waitcnt lgkmcnt(0)
	ds_read_b128 v[244:247], v188 offset:32896
	ds_read_b128 v[248:251], v188 offset:45184
	v_add_f32_e32 v162, v162, v110
	v_cvt_pk_bf16_f32 v112, v112, v113
	v_cvt_pk_bf16_f32 v113, v114, v115
	v_cvt_pk_bf16_f32 v114, v116, v117
	v_mfma_f32_32x32x16_bf16 v[80:95], v[232:235], v[152:155], v[80:95]
	v_cvt_pk_bf16_f32 v115, v118, v119
	v_add_f32_e32 v231, v111, v162
	v_permlane32_swap_b32_e32 v112, v114
	v_permlane32_swap_b32_e32 v113, v115
	v_mfma_f32_32x32x16_bf16 v[64:79], v[236:239], v[152:155], v[64:79]
	s_waitcnt lgkmcnt(0)
	ds_read_b128 v[232:235], v190 offset:32896
	ds_read_b128 v[236:239], v190 offset:45184
	v_cvt_pk_bf16_f32 v116, v120, v121
	v_cvt_pk_bf16_f32 v117, v122, v123
	v_cvt_pk_bf16_f32 v118, v124, v125
	v_mfma_f32_32x32x16_bf16 v[80:95], v[244:247], v[148:151], v[80:95]
	v_cvt_pk_bf16_f32 v119, v126, v127
	v_permlane32_swap_b32_e32 v116, v118
	v_mfma_f32_32x32x16_bf16 v[64:79], v[248:251], v[148:151], v[64:79]
	v_permlane32_swap_b32_e32 v117, v119
	s_waitcnt lgkmcnt(0)
	ds_read_b128 v[244:247], v192 offset:32896
	ds_read_b128 v[248:251], v192 offset:45184
	v_cvt_pk_bf16_f32 v96, v96, v97
	v_cvt_pk_bf16_f32 v97, v98, v99
	v_cvt_pk_bf16_f32 v98, v100, v101
	v_mfma_f32_32x32x16_bf16 v[80:95], v[232:235], v[144:147], v[80:95]
	v_cvt_pk_bf16_f32 v99, v102, v103
	v_permlane32_swap_b32_e32 v96, v98
	v_mfma_f32_32x32x16_bf16 v[64:79], v[236:239], v[144:147], v[64:79]
	v_permlane32_swap_b32_e32 v97, v99
	s_waitcnt lgkmcnt(0)
; #define LAS __attribute__((address_space(3)))
; __device__ __forceinline__ float fma_s(float a, float b, float c) { float d; asm volatile("v_fma_f32 %0, %1, %2, %3" : "=v"(d) : "v"(a), "v"(b), "v"(c)); return d; }
; template <int S> __device__ __forceinline__ void psm_chunk(f32x16& p0, f32x16& p1, float& mx, float& m_reg, float& alpha, float& mnC) {
;   constexpr float C = SCALE * 1.4426950408889634f; const float Cv = C;
;   if constexpr (S == 0) { mx = p0[0];
; #pragma unroll
;     for (int r = 1; r < 16; ++r) mx = fmaxf(mx, p0[r]); }
;   else if constexpr (S == 1) {
; #pragma unroll
;     for (int r = 0; r < 16; ++r) mx = fmaxf(mx, p1[r]);
;     { auto rr = __builtin_amdgcn_permlane32_swap(__float_as_uint(mx), __float_as_uint(mx), false, false); mx = fmaxf(__uint_as_float(rr[0]), __uint_as_float(rr[1])); }
;     const float mn = (mx - m_reg > THR / SCALE) ? fmaxf(m_reg, mx) : m_reg; alpha = __builtin_amdgcn_exp2f((m_reg - mn) * C); m_reg = mn; mnC = -mn * C; }
;   else if constexpr (S == 2) {
; #pragma unroll
;     for (int r = 0; r < 8; ++r) p0[r] = fma_s(p0[r], Cv, mnC); }
;   else if constexpr (S == 3) {
; #pragma unroll
;     for (int r = 8; r < 16; ++r) p0[r] = fma_s(p0[r], Cv, mnC);
; #pragma unroll
;     for (int r = 0; r < 4; ++r) p0[r] = __builtin_amdgcn_exp2f(p0[r]); }
;   else if constexpr (S == 4) {
; #pragma unroll
;     for (int r = 0; r < 8; ++r) p1[r] = fma_s(p1[r], Cv, mnC);
; #pragma unroll
;     for (int r = 4; r < 8; ++r) p0[r] = __builtin_amdgcn_exp2f(p0[r]); }
;   else if constexpr (S == 5) {
; #pragma unroll
;     for (int r = 8; r < 16; ++r) p1[r] = fma_s(p1[r], Cv, mnC);
; #pragma unroll
;     for (int r = 8; r < 12; ++r) p0[r] = __builtin_amdgcn_exp2f(p0[r]); }
;   else if constexpr (S == 6) {
; #pragma unroll
;     for (int r = 12; r < 16; ++r) p0[r] = __builtin_amdgcn_exp2f(p0[r]); }
;   if constexpr (S == 0 || S == 1) asm volatile("" : "+v"(mx), "+v"(alpha), "+v"(mnC), "+v"(m_reg));
;   else if constexpr (S < 7) asm volatile("" : "+v"(p0), "+v"(p1));
; }
; __device__ __forceinline__ void pv_psm(f32x16* o, const LAS char* vl, bf16x8 pa0, bf16x8 pa1, bf16x8 pa2, bf16x8 pa3, f32x16& n0, f32x16& n1, float& m_reg, float& alN) {
;   float mx = 0.f, mnC = 0.f;
;     ...
;   VSLOT(0) VSLOT(1) VSLOT(2) VSLOT(3) VSLOT(4) VSLOT(5) VSLOT(6) VSLOT(7)
	ds_read_b64_tr_b16 v[232:233], v184 offset:16384
	ds_read_b64_tr_b16 v[234:235], v184 offset:18432
	ds_read_b64_tr_b16 v[236:237], v184 offset:20480
	ds_read_b64_tr_b16 v[238:239], v184 offset:22528
	v_cvt_pk_bf16_f32 v100, v104, v105
	v_cvt_pk_bf16_f32 v101, v106, v107
	v_cvt_pk_bf16_f32 v102, v108, v109
	v_mfma_f32_32x32x16_bf16 v[80:95], v[244:247], v[140:143], v[80:95]
	v_cvt_pk_bf16_f32 v103, v110, v111
	v_permlane32_swap_b32_e32 v100, v102
	v_mfma_f32_32x32x16_bf16 v[64:79], v[248:251], v[140:143], v[64:79]
	v_permlane32_swap_b32_e32 v101, v103
	v_mov_b32_e32 v104, v231
	s_nop 1
	v_permlane32_swap_b32_e32 v231, v104
	s_waitcnt lgkmcnt(0)
	ds_read_b64_tr_b16 v[106:107], v184 offset:24576
	ds_read_b64_tr_b16 v[108:109], v184 offset:26624
	ds_read_b64_tr_b16 v[120:121], v184 offset:28672
	ds_read_b64_tr_b16 v[122:123], v184 offset:30720
	v_max_f32_e32 v105, v81, v81
	v_max_f32_e32 v110, v80, v80
	v_mfma_f32_32x32x16_bf16 v[0:15], v[112:115], v[232:235], v[0:15]
	v_max_f32_e32 v105, v110, v105
	v_max3_f32 v105, v105, v82, v83
	v_max3_f32 v105, v105, v84, v85
	v_max3_f32 v105, v105, v86, v87
	v_max3_f32 v105, v105, v88, v89
	v_max3_f32 v105, v105, v90, v91
	v_max3_f32 v105, v105, v92, v93
	v_mfma_f32_32x32x16_bf16 v[0:15], v[116:119], v[236:239], v[0:15]
	v_max3_f32 v105, v105, v94, v95
	s_waitcnt lgkmcnt(0)
	ds_read_b64_tr_b16 v[232:233], v184 offset:16896
	ds_read_b64_tr_b16 v[234:235], v184 offset:18944
	ds_read_b64_tr_b16 v[236:237], v184 offset:20992
	ds_read_b64_tr_b16 v[238:239], v184 offset:23040
	v_max3_f32 v105, v105, v64, v65
	v_max3_f32 v105, v105, v66, v67
	v_max3_f32 v105, v105, v68, v69
	v_max3_f32 v105, v105, v70, v71
	v_mfma_f32_32x32x16_bf16 v[0:15], v[96:99], v[106:109], v[0:15]
	v_max3_f32 v105, v105, v72, v73
	v_max3_f32 v105, v105, v74, v75
	v_max3_f32 v105, v105, v76, v77
	v_max3_f32 v105, v105, v78, v79
	v_mov_b32_e32 v110, v105
	s_nop 1
	v_permlane32_swap_b32_e32 v105, v110
	v_max_f32_e32 v110, v110, v110
	v_max_f32_e32 v105, v105, v105
	v_max_f32_e32 v105, v105, v110
	v_mfma_f32_32x32x16_bf16 v[0:15], v[100:103], v[120:123], v[0:15]
	v_sub_f32_e32 v110, v105, v230
	v_cmp_lt_f32_e32 vcc, s29, v110
	v_max_f32_e32 v110, v230, v230
	v_max_f32_e32 v110, v110, v105
	v_cndmask_b32_e32 v228, v230, v110, vcc
	v_sub_f32_e32 v110, v230, v228
	v_mul_f32_e32 v110, 0x3dd53b94, v110
	v_exp_f32_e32 v162, v110
	v_mul_f32_e32 v110, 0xbdd53b94, v228
	s_waitcnt lgkmcnt(0)
	ds_read_b64_tr_b16 v[106:107], v184 offset:25088
	ds_read_b64_tr_b16 v[108:109], v184 offset:27136
	ds_read_b64_tr_b16 v[120:121], v184 offset:29184
	ds_read_b64_tr_b16 v[122:123], v184 offset:31232
	v_fma_f32 v80, v80, v211, v110
	v_fma_f32 v81, v81, v211, v110
	v_mfma_f32_32x32x16_bf16 v[48:63], v[112:115], v[232:235], v[48:63]
	v_fma_f32 v82, v82, v211, v110
	v_fma_f32 v83, v83, v211, v110
	v_fma_f32 v84, v84, v211, v110
	v_fma_f32 v85, v85, v211, v110
	v_fma_f32 v86, v86, v211, v110
	v_fma_f32 v87, v87, v211, v110
	v_mfma_f32_32x32x16_bf16 v[48:63], v[116:119], v[236:239], v[48:63]
	s_waitcnt lgkmcnt(0)
	ds_read_b64_tr_b16 v[232:233], v184 offset:17408
	ds_read_b64_tr_b16 v[234:235], v184 offset:19456
	ds_read_b64_tr_b16 v[236:237], v184 offset:21504
	ds_read_b64_tr_b16 v[238:239], v184 offset:23552
	v_fma_f32 v88, v88, v211, v110
	v_fma_f32 v89, v89, v211, v110
	v_mfma_f32_32x32x16_bf16 v[48:63], v[96:99], v[106:109], v[48:63]
	v_fma_f32 v90, v90, v211, v110
	v_fma_f32 v91, v91, v211, v110
	v_fma_f32 v92, v92, v211, v110
	v_exp_f32_e32 v80, v80
	v_exp_f32_e32 v81, v81
	v_exp_f32_e32 v82, v82
	v_exp_f32_e32 v83, v83
	v_mfma_f32_32x32x16_bf16 v[48:63], v[100:103], v[120:123], v[48:63]
	v_fma_f32 v93, v93, v211, v110
	v_fma_f32 v94, v94, v211, v110
	v_fma_f32 v95, v95, v211, v110
	s_nop 0
	s_waitcnt lgkmcnt(0)
	ds_read_b64_tr_b16 v[106:107], v184 offset:25600
	ds_read_b64_tr_b16 v[108:109], v184 offset:27648
	ds_read_b64_tr_b16 v[120:121], v184 offset:29696
	ds_read_b64_tr_b16 v[122:123], v184 offset:31744
	v_fma_f32 v64, v64, v211, v110
	v_fma_f32 v65, v65, v211, v110
	v_mfma_f32_32x32x16_bf16 v[32:47], v[112:115], v[232:235], v[32:47]
	v_fma_f32 v66, v66, v211, v110
	v_fma_f32 v67, v67, v211, v110
	v_fma_f32 v68, v68, v211, v110
	v_exp_f32_e32 v84, v84
	v_exp_f32_e32 v85, v85
	v_exp_f32_e32 v86, v86
	v_exp_f32_e32 v87, v87
	v_mfma_f32_32x32x16_bf16 v[32:47], v[116:119], v[236:239], v[32:47]
	v_fma_f32 v69, v69, v211, v110
	v_fma_f32 v70, v70, v211, v110
	v_fma_f32 v71, v71, v211, v110
	s_nop 0
	s_waitcnt lgkmcnt(0)
	ds_read_b64_tr_b16 v[232:233], v184 offset:17920
	ds_read_b64_tr_b16 v[234:235], v184 offset:19968
	ds_read_b64_tr_b16 v[236:237], v184 offset:22016
	ds_read_b64_tr_b16 v[238:239], v184 offset:24064
	v_fma_f32 v72, v72, v211, v110
	v_fma_f32 v73, v73, v211, v110
	v_mfma_f32_32x32x16_bf16 v[32:47], v[96:99], v[106:109], v[32:47]
	v_fma_f32 v74, v74, v211, v110
	v_fma_f32 v75, v75, v211, v110
	v_fma_f32 v76, v76, v211, v110
	v_exp_f32_e32 v88, v88
	v_exp_f32_e32 v89, v89
	v_exp_f32_e32 v90, v90
	v_exp_f32_e32 v91, v91
	v_mfma_f32_32x32x16_bf16 v[32:47], v[100:103], v[120:123], v[32:47]
	v_fma_f32 v77, v77, v211, v110
	v_fma_f32 v78, v78, v211, v110
	v_fma_f32 v79, v79, v211, v110
	s_nop 0
	s_waitcnt lgkmcnt(0)
	ds_read_b64_tr_b16 v[106:107], v184 offset:26112
	ds_read_b64_tr_b16 v[108:109], v184 offset:28160
	ds_read_b64_tr_b16 v[120:121], v184 offset:30208
	ds_read_b64_tr_b16 v[122:123], v184 offset:32256
	v_exp_f32_e32 v92, v92
	v_exp_f32_e32 v93, v93
	v_mfma_f32_32x32x16_bf16 v[16:31], v[112:115], v[232:235], v[16:31]
	v_exp_f32_e32 v94, v94
	v_exp_f32_e32 v95, v95
	v_mfma_f32_32x32x16_bf16 v[16:31], v[116:119], v[236:239], v[16:31]
	s_waitcnt lgkmcnt(0)
	s_add_i32 s24, s24, 2
	s_add_u32 s31, s31, 0xc000
	s_addc_u32 s9, s9, 0
	v_add_f32_e32 v252, v227, v229
	s_add_u32 s90, s90, 0x8000
	v_fmac_f32_e32 v252, v224, v171
	v_add_f32_e32 v171, v231, v104
	s_addc_u32 s91, s91, 0
	v_fmac_f32_e32 v171, v252, v223
	v_cmp_gt_f32_e32 vcc, 1.0, v162
	s_waitcnt vmcnt(0) lgkmcnt(0)
	s_barrier
; __device__ __forceinline__ void attn_unit(const bf16_t* __restrict__ Qb, const bf16_t* __restrict__ Kh, const bf16_t* __restrict__ Vh, bf16_t* __restrict__ Ob, float* __restrict__ ssq, char* lds, LAS unsigned char* ldsl, ...
;     ...
;   for (int j = 0; j < NT - 2; j += 2) {
;     STEP(pA0, pA1, alA, pB0, pB1, mnB, alB, j, true, true);
;     STEP(pB0, pB1, alB, pA0, pA1, mnA, alA, j + 1, true, true);
;   }
	ds_read_b128 v[230:233], v186 offset:57344
	ds_read_b128 v[234:237], v187 offset:12288
	v_mfma_f32_32x32x16_bf16 v[16:31], v[96:99], v[106:109], v[16:31]
	v_mfma_f32_32x32x16_bf16 v[16:31], v[100:103], v[120:123], v[16:31]
	s_cbranch_vccz .LBB0_1019
	s_and_saveexec_b64 s[6:7], s[40:41]
	ds_write_b32 v185, v162 offset:128
	s_or_b64 exec, exec, s[6:7]
	s_waitcnt lgkmcnt(0)
	ds_read_b128 v[96:99], v196 offset:224
	ds_read_b128 v[100:103], v196 offset:192
	ds_read_b128 v[106:109], v196 offset:160
	ds_read_b128 v[110:113], v196 offset:128
	s_waitcnt lgkmcnt(0)
	v_pk_mul_f32 v[12:13], v[12:13], v[96:97]
	v_pk_mul_f32 v[8:9], v[8:9], v[100:101]
	v_pk_mul_f32 v[4:5], v[4:5], v[106:107]
	v_pk_mul_f32 v[14:15], v[14:15], v[98:99]
	v_pk_mul_f32 v[10:11], v[10:11], v[102:103]
	v_pk_mul_f32 v[6:7], v[6:7], v[108:109]
	v_pk_mul_f32 v[2:3], v[2:3], v[112:113]
	v_pk_mul_f32 v[0:1], v[0:1], v[110:111]
	v_pk_mul_f32 v[60:61], v[60:61], v[96:97]
	v_pk_mul_f32 v[56:57], v[56:57], v[100:101]
	v_pk_mul_f32 v[52:53], v[52:53], v[106:107]
	v_pk_mul_f32 v[62:63], v[62:63], v[98:99]
	v_pk_mul_f32 v[58:59], v[58:59], v[102:103]
	v_pk_mul_f32 v[54:55], v[54:55], v[108:109]
	v_pk_mul_f32 v[50:51], v[50:51], v[112:113]
	v_pk_mul_f32 v[48:49], v[48:49], v[110:111]
	v_pk_mul_f32 v[44:45], v[44:45], v[96:97]
	v_pk_mul_f32 v[40:41], v[40:41], v[100:101]
	v_pk_mul_f32 v[36:37], v[36:37], v[106:107]
	v_pk_mul_f32 v[46:47], v[46:47], v[98:99]
	v_pk_mul_f32 v[42:43], v[42:43], v[102:103]
	v_pk_mul_f32 v[38:39], v[38:39], v[108:109]
	v_pk_mul_f32 v[34:35], v[34:35], v[112:113]
	v_pk_mul_f32 v[32:33], v[32:33], v[110:111]
	v_pk_mul_f32 v[28:29], v[28:29], v[96:97]
	v_pk_mul_f32 v[24:25], v[24:25], v[100:101]
	v_pk_mul_f32 v[20:21], v[20:21], v[106:107]
	v_pk_mul_f32 v[30:31], v[30:31], v[98:99]
	v_pk_mul_f32 v[26:27], v[26:27], v[102:103]
	v_pk_mul_f32 v[22:23], v[22:23], v[108:109]
	v_pk_mul_f32 v[18:19], v[18:19], v[112:113]
	v_pk_mul_f32 v[16:17], v[16:17], v[110:111]
.LBB0_1019:
	s_cmpk_gt_u32 s24, 0x7b
	s_cbranch_scc1 .LBB0_1021
	v_mov_b32_e32 v224, v162
	s_branch .LBB0_1011
